# fuse final LayerNorm into MLP-down GEMM tile epilogue (values stay in registers; row stats exchanged between the 4 column-tile workgroups); P12 only for sample rows
# speedup vs baseline: 1.0169x; 1.0169x over previous
; __device__ __forceinline__ void ssm_tables(const Params& p, int g, int part, LAS float* sm, int tid) {
;     ...
;         for (int e = tid; e < 2048; e += 512) { const int l = e >> 8, pch = (e >> 4) & 15, q = e & 15; float s = 0.f;
;             for (int n = 0; n < 64; ++n) { const float cr = cre[pch * 64 + n], ci = cim[pch * 64 + n], ar = pwr[l * 64 + n], ai = pwi[l * 64 + n];
;                 const float zr = cr * ar - ci * ai, zi = cr * ai + ci * ar; s += zr * bbr[n * 16 + q] - zi * bbi[n * 16 + q]; }
;             kc[e] = s; }
.LBB0_236:
	v_add_u32_e32 v108, 0x1000, v19
	ds_read_b128 v[80:83], v16 offset:0
	ds_read_b128 v[84:87], v16 offset:4096
	ds_read_b128 v[88:91], v17 offset:0
	ds_read_b128 v[92:95], v17 offset:2304
	ds_read2_b32 v[96:97], v19 offset1:16
	ds_read2_b32 v[98:99], v19 offset0:32 offset1:48
	ds_read2_b32 v[100:101], v108 offset1:16
	ds_read2_b32 v[102:103], v108 offset0:32 offset1:48
	v_add_u32_e32 v107, 0x100, v19
	v_add_u32_e32 v108, 0x1100, v19
	ds_read_b128 v[130:133], v16 offset:16
	ds_read_b128 v[134:137], v16 offset:4112
	ds_read_b128 v[138:141], v17 offset:16
	ds_read_b128 v[142:145], v17 offset:2320
	ds_read2_b32 v[146:147], v107 offset1:16
	ds_read2_b32 v[148:149], v107 offset0:32 offset1:48
	ds_read2_b32 v[150:151], v108 offset1:16
	ds_read2_b32 v[152:153], v108 offset0:32 offset1:48
	s_waitcnt lgkmcnt(8)
	v_mul_f32_e32 v104, v84, v92
	v_mul_f32_e32 v105, v84, v88
	v_fma_f32 v104, v80, v88, -v104
	v_fmac_f32_e32 v105, v80, v92
	v_mul_f32_e32 v106, v105, v100
	v_fma_f32 v106, v104, v96, -v106
	v_add_f32_e32 v18, v18, v106
	v_mul_f32_e32 v104, v85, v93
	v_mul_f32_e32 v105, v85, v89
	v_fma_f32 v104, v81, v89, -v104
	v_fmac_f32_e32 v105, v81, v93
	v_mul_f32_e32 v106, v105, v101
	v_fma_f32 v106, v104, v97, -v106
	v_add_f32_e32 v18, v18, v106
	v_mul_f32_e32 v104, v86, v94
	v_mul_f32_e32 v105, v86, v90
	v_fma_f32 v104, v82, v90, -v104
	v_fmac_f32_e32 v105, v82, v94
	v_mul_f32_e32 v106, v105, v102
	v_fma_f32 v106, v104, v98, -v106
	v_add_f32_e32 v18, v18, v106
	v_mul_f32_e32 v104, v87, v95
	v_mul_f32_e32 v105, v87, v91
	v_fma_f32 v104, v83, v91, -v104
	v_fmac_f32_e32 v105, v83, v95
	v_mul_f32_e32 v106, v105, v103
	v_fma_f32 v106, v104, v99, -v106
	v_add_f32_e32 v18, v18, v106
	v_add_u32_e32 v107, 0x200, v19
	v_add_u32_e32 v108, 0x1200, v19
	ds_read_b128 v[80:83], v16 offset:32
	ds_read_b128 v[84:87], v16 offset:4128
	ds_read_b128 v[88:91], v17 offset:32
	ds_read_b128 v[92:95], v17 offset:2336
	ds_read2_b32 v[96:97], v107 offset1:16
	ds_read2_b32 v[98:99], v107 offset0:32 offset1:48
	ds_read2_b32 v[100:101], v108 offset1:16
	ds_read2_b32 v[102:103], v108 offset0:32 offset1:48
	s_waitcnt lgkmcnt(8)
	v_mul_f32_e32 v104, v134, v142
	v_mul_f32_e32 v105, v134, v138
	v_fma_f32 v104, v130, v138, -v104
	v_fmac_f32_e32 v105, v130, v142
	v_mul_f32_e32 v106, v105, v150
	v_fma_f32 v106, v104, v146, -v106
	v_add_f32_e32 v18, v18, v106
	v_mul_f32_e32 v104, v135, v143
	v_mul_f32_e32 v105, v135, v139
	v_fma_f32 v104, v131, v139, -v104
	v_fmac_f32_e32 v105, v131, v143
	v_mul_f32_e32 v106, v105, v151
	v_fma_f32 v106, v104, v147, -v106
	v_add_f32_e32 v18, v18, v106
	v_mul_f32_e32 v104, v136, v144
	v_mul_f32_e32 v105, v136, v140
	v_fma_f32 v104, v132, v140, -v104
	v_fmac_f32_e32 v105, v132, v144
	v_mul_f32_e32 v106, v105, v152
	v_fma_f32 v106, v104, v148, -v106
	v_add_f32_e32 v18, v18, v106
	v_mul_f32_e32 v104, v137, v145
	v_mul_f32_e32 v105, v137, v141
	v_fma_f32 v104, v133, v141, -v104
	v_fmac_f32_e32 v105, v133, v145
	v_mul_f32_e32 v106, v105, v153
	v_fma_f32 v106, v104, v149, -v106
	v_add_f32_e32 v18, v18, v106
	v_add_u32_e32 v107, 0x300, v19
	v_add_u32_e32 v108, 0x1300, v19
	ds_read_b128 v[130:133], v16 offset:48
	ds_read_b128 v[134:137], v16 offset:4144
	ds_read_b128 v[138:141], v17 offset:48
	ds_read_b128 v[142:145], v17 offset:2352
	ds_read2_b32 v[146:147], v107 offset1:16
	ds_read2_b32 v[148:149], v107 offset0:32 offset1:48
	ds_read2_b32 v[150:151], v108 offset1:16
	ds_read2_b32 v[152:153], v108 offset0:32 offset1:48
	s_waitcnt lgkmcnt(8)
	v_mul_f32_e32 v104, v84, v92
	v_mul_f32_e32 v105, v84, v88
	v_fma_f32 v104, v80, v88, -v104
	v_fmac_f32_e32 v105, v80, v92
	v_mul_f32_e32 v106, v105, v100
	v_fma_f32 v106, v104, v96, -v106
	v_add_f32_e32 v18, v18, v106
	v_mul_f32_e32 v104, v85, v93
	v_mul_f32_e32 v105, v85, v89
	v_fma_f32 v104, v81, v89, -v104
	v_fmac_f32_e32 v105, v81, v93
	v_mul_f32_e32 v106, v105, v101
	v_fma_f32 v106, v104, v97, -v106
	v_add_f32_e32 v18, v18, v106
	v_mul_f32_e32 v104, v86, v94
	v_mul_f32_e32 v105, v86, v90
	v_fma_f32 v104, v82, v90, -v104
	v_fmac_f32_e32 v105, v82, v94
	v_mul_f32_e32 v106, v105, v102
	v_fma_f32 v106, v104, v98, -v106
	v_add_f32_e32 v18, v18, v106
	v_mul_f32_e32 v104, v87, v95
	v_mul_f32_e32 v105, v87, v91
	v_fma_f32 v104, v83, v91, -v104
	v_fmac_f32_e32 v105, v83, v95
	v_mul_f32_e32 v106, v105, v103
	v_fma_f32 v106, v104, v99, -v106
	v_add_f32_e32 v18, v18, v106
	v_add_u32_e32 v107, 0x400, v19
	v_add_u32_e32 v108, 0x1400, v19
	ds_read_b128 v[80:83], v16 offset:64
	ds_read_b128 v[84:87], v16 offset:4160
	ds_read_b128 v[88:91], v17 offset:64
	ds_read_b128 v[92:95], v17 offset:2368
	ds_read2_b32 v[96:97], v107 offset1:16
	ds_read2_b32 v[98:99], v107 offset0:32 offset1:48
	ds_read2_b32 v[100:101], v108 offset1:16
	ds_read2_b32 v[102:103], v108 offset0:32 offset1:48
	s_waitcnt lgkmcnt(8)
	v_mul_f32_e32 v104, v134, v142
	v_mul_f32_e32 v105, v134, v138
	v_fma_f32 v104, v130, v138, -v104
	v_fmac_f32_e32 v105, v130, v142
	v_mul_f32_e32 v106, v105, v150
	v_fma_f32 v106, v104, v146, -v106
	v_add_f32_e32 v18, v18, v106
	v_mul_f32_e32 v104, v135, v143
	v_mul_f32_e32 v105, v135, v139
	v_fma_f32 v104, v131, v139, -v104
	v_fmac_f32_e32 v105, v131, v143
	v_mul_f32_e32 v106, v105, v151
	v_fma_f32 v106, v104, v147, -v106
	v_add_f32_e32 v18, v18, v106
	v_mul_f32_e32 v104, v136, v144
	v_mul_f32_e32 v105, v136, v140
	v_fma_f32 v104, v132, v140, -v104
	v_fmac_f32_e32 v105, v132, v144
	v_mul_f32_e32 v106, v105, v152
	v_fma_f32 v106, v104, v148, -v106
	v_add_f32_e32 v18, v18, v106
	v_mul_f32_e32 v104, v137, v145
	v_mul_f32_e32 v105, v137, v141
	v_fma_f32 v104, v133, v141, -v104
	v_fmac_f32_e32 v105, v133, v145
	v_mul_f32_e32 v106, v105, v153
	v_fma_f32 v106, v104, v149, -v106
	v_add_f32_e32 v18, v18, v106
	v_add_u32_e32 v107, 0x500, v19
	v_add_u32_e32 v108, 0x1500, v19
	ds_read_b128 v[130:133], v16 offset:80
	ds_read_b128 v[134:137], v16 offset:4176
	ds_read_b128 v[138:141], v17 offset:80
	ds_read_b128 v[142:145], v17 offset:2384
	ds_read2_b32 v[146:147], v107 offset1:16
	ds_read2_b32 v[148:149], v107 offset0:32 offset1:48
	ds_read2_b32 v[150:151], v108 offset1:16
	ds_read2_b32 v[152:153], v108 offset0:32 offset1:48
	s_waitcnt lgkmcnt(8)
; __device__ __forceinline__ void ssm_tables(const Params& p, int g, int part, LAS float* sm, int tid) {
;     ...
;         for (int e = tid; e < 2048; e += 512) { const int l = e >> 8, pch = (e >> 4) & 15, q = e & 15; float s = 0.f;
;             for (int n = 0; n < 64; ++n) { const float cr = cre[pch * 64 + n], ci = cim[pch * 64 + n], ar = pwr[l * 64 + n], ai = pwi[l * 64 + n];
;                 const float zr = cr * ar - ci * ai, zi = cr * ai + ci * ar; s += zr * bbr[n * 16 + q] - zi * bbi[n * 16 + q]; }
;             kc[e] = s; }
	v_mul_f32_e32 v104, v84, v92
	v_mul_f32_e32 v105, v84, v88
	v_fma_f32 v104, v80, v88, -v104
	v_fmac_f32_e32 v105, v80, v92
	v_mul_f32_e32 v106, v105, v100
	v_fma_f32 v106, v104, v96, -v106
	v_add_f32_e32 v18, v18, v106
	v_mul_f32_e32 v104, v85, v93
	v_mul_f32_e32 v105, v85, v89
	v_fma_f32 v104, v81, v89, -v104
	v_fmac_f32_e32 v105, v81, v93
	v_mul_f32_e32 v106, v105, v101
	v_fma_f32 v106, v104, v97, -v106
	v_add_f32_e32 v18, v18, v106
	v_mul_f32_e32 v104, v86, v94
	v_mul_f32_e32 v105, v86, v90
	v_fma_f32 v104, v82, v90, -v104
	v_fmac_f32_e32 v105, v82, v94
	v_mul_f32_e32 v106, v105, v102
	v_fma_f32 v106, v104, v98, -v106
	v_add_f32_e32 v18, v18, v106
	v_mul_f32_e32 v104, v87, v95
	v_mul_f32_e32 v105, v87, v91
	v_fma_f32 v104, v83, v91, -v104
	v_fmac_f32_e32 v105, v83, v95
	v_mul_f32_e32 v106, v105, v103
	v_fma_f32 v106, v104, v99, -v106
	v_add_f32_e32 v18, v18, v106
	v_add_u32_e32 v107, 0x600, v19
	v_add_u32_e32 v108, 0x1600, v19
	ds_read_b128 v[80:83], v16 offset:96
	ds_read_b128 v[84:87], v16 offset:4192
	ds_read_b128 v[88:91], v17 offset:96
	ds_read_b128 v[92:95], v17 offset:2400
	ds_read2_b32 v[96:97], v107 offset1:16
	ds_read2_b32 v[98:99], v107 offset0:32 offset1:48
	ds_read2_b32 v[100:101], v108 offset1:16
	ds_read2_b32 v[102:103], v108 offset0:32 offset1:48
	s_waitcnt lgkmcnt(8)
	v_mul_f32_e32 v104, v134, v142
	v_mul_f32_e32 v105, v134, v138
	v_fma_f32 v104, v130, v138, -v104
	v_fmac_f32_e32 v105, v130, v142
	v_mul_f32_e32 v106, v105, v150
	v_fma_f32 v106, v104, v146, -v106
	v_add_f32_e32 v18, v18, v106
	v_mul_f32_e32 v104, v135, v143
	v_mul_f32_e32 v105, v135, v139
	v_fma_f32 v104, v131, v139, -v104
	v_fmac_f32_e32 v105, v131, v143
	v_mul_f32_e32 v106, v105, v151
	v_fma_f32 v106, v104, v147, -v106
	v_add_f32_e32 v18, v18, v106
	v_mul_f32_e32 v104, v136, v144
	v_mul_f32_e32 v105, v136, v140
	v_fma_f32 v104, v132, v140, -v104
	v_fmac_f32_e32 v105, v132, v144
	v_mul_f32_e32 v106, v105, v152
	v_fma_f32 v106, v104, v148, -v106
	v_add_f32_e32 v18, v18, v106
	v_mul_f32_e32 v104, v137, v145
	v_mul_f32_e32 v105, v137, v141
	v_fma_f32 v104, v133, v141, -v104
	v_fmac_f32_e32 v105, v133, v145
	v_mul_f32_e32 v106, v105, v153
	v_fma_f32 v106, v104, v149, -v106
	v_add_f32_e32 v18, v18, v106
	v_add_u32_e32 v107, 0x700, v19
	v_add_u32_e32 v108, 0x1700, v19
	ds_read_b128 v[130:133], v16 offset:112
	ds_read_b128 v[134:137], v16 offset:4208
	ds_read_b128 v[138:141], v17 offset:112
	ds_read_b128 v[142:145], v17 offset:2416
	ds_read2_b32 v[146:147], v107 offset1:16
	ds_read2_b32 v[148:149], v107 offset0:32 offset1:48
	ds_read2_b32 v[150:151], v108 offset1:16
	ds_read2_b32 v[152:153], v108 offset0:32 offset1:48
	s_waitcnt lgkmcnt(8)
	v_mul_f32_e32 v104, v84, v92
	v_mul_f32_e32 v105, v84, v88
	v_fma_f32 v104, v80, v88, -v104
	v_fmac_f32_e32 v105, v80, v92
	v_mul_f32_e32 v106, v105, v100
	v_fma_f32 v106, v104, v96, -v106
	v_add_f32_e32 v18, v18, v106
	v_mul_f32_e32 v104, v85, v93
	v_mul_f32_e32 v105, v85, v89
	v_fma_f32 v104, v81, v89, -v104
	v_fmac_f32_e32 v105, v81, v93
	v_mul_f32_e32 v106, v105, v101
	v_fma_f32 v106, v104, v97, -v106
	v_add_f32_e32 v18, v18, v106
	v_mul_f32_e32 v104, v86, v94
	v_mul_f32_e32 v105, v86, v90
	v_fma_f32 v104, v82, v90, -v104
	v_fmac_f32_e32 v105, v82, v94
	v_mul_f32_e32 v106, v105, v102
	v_fma_f32 v106, v104, v98, -v106
	v_add_f32_e32 v18, v18, v106
	v_mul_f32_e32 v104, v87, v95
	v_mul_f32_e32 v105, v87, v91
	v_fma_f32 v104, v83, v91, -v104
	v_fmac_f32_e32 v105, v83, v95
	v_mul_f32_e32 v106, v105, v103
	v_fma_f32 v106, v104, v99, -v106
	v_add_f32_e32 v18, v18, v106
	v_add_u32_e32 v107, 0x800, v19
	v_add_u32_e32 v108, 0x1800, v19
	ds_read_b128 v[80:83], v16 offset:128
	ds_read_b128 v[84:87], v16 offset:4224
	ds_read_b128 v[88:91], v17 offset:128
	ds_read_b128 v[92:95], v17 offset:2432
	ds_read2_b32 v[96:97], v107 offset1:16
	ds_read2_b32 v[98:99], v107 offset0:32 offset1:48
	ds_read2_b32 v[100:101], v108 offset1:16
	ds_read2_b32 v[102:103], v108 offset0:32 offset1:48
	s_waitcnt lgkmcnt(8)
	v_mul_f32_e32 v104, v134, v142
	v_mul_f32_e32 v105, v134, v138
	v_fma_f32 v104, v130, v138, -v104
	v_fmac_f32_e32 v105, v130, v142
	v_mul_f32_e32 v106, v105, v150
	v_fma_f32 v106, v104, v146, -v106
	v_add_f32_e32 v18, v18, v106
	v_mul_f32_e32 v104, v135, v143
	v_mul_f32_e32 v105, v135, v139
	v_fma_f32 v104, v131, v139, -v104
	v_fmac_f32_e32 v105, v131, v143
	v_mul_f32_e32 v106, v105, v151
	v_fma_f32 v106, v104, v147, -v106
	v_add_f32_e32 v18, v18, v106
	v_mul_f32_e32 v104, v136, v144
	v_mul_f32_e32 v105, v136, v140
	v_fma_f32 v104, v132, v140, -v104
	v_fmac_f32_e32 v105, v132, v144
	v_mul_f32_e32 v106, v105, v152
	v_fma_f32 v106, v104, v148, -v106
	v_add_f32_e32 v18, v18, v106
	v_mul_f32_e32 v104, v137, v145
	v_mul_f32_e32 v105, v137, v141
	v_fma_f32 v104, v133, v141, -v104
	v_fmac_f32_e32 v105, v133, v145
	v_mul_f32_e32 v106, v105, v153
	v_fma_f32 v106, v104, v149, -v106
	v_add_f32_e32 v18, v18, v106
	v_add_u32_e32 v107, 0x900, v19
	v_add_u32_e32 v108, 0x1900, v19
	ds_read_b128 v[130:133], v16 offset:144
	ds_read_b128 v[134:137], v16 offset:4240
	ds_read_b128 v[138:141], v17 offset:144
	ds_read_b128 v[142:145], v17 offset:2448
	ds_read2_b32 v[146:147], v107 offset1:16
	ds_read2_b32 v[148:149], v107 offset0:32 offset1:48
	ds_read2_b32 v[150:151], v108 offset1:16
	ds_read2_b32 v[152:153], v108 offset0:32 offset1:48
	s_waitcnt lgkmcnt(8)
; __device__ __forceinline__ void ssm_tables(const Params& p, int g, int part, LAS float* sm, int tid) {
;     ...
;         for (int e = tid; e < 2048; e += 512) { const int l = e >> 8, pch = (e >> 4) & 15, q = e & 15; float s = 0.f;
;             for (int n = 0; n < 64; ++n) { const float cr = cre[pch * 64 + n], ci = cim[pch * 64 + n], ar = pwr[l * 64 + n], ai = pwi[l * 64 + n];
;                 const float zr = cr * ar - ci * ai, zi = cr * ai + ci * ar; s += zr * bbr[n * 16 + q] - zi * bbi[n * 16 + q]; }
;             kc[e] = s; }
	v_mul_f32_e32 v104, v84, v92
	v_mul_f32_e32 v105, v84, v88
	v_fma_f32 v104, v80, v88, -v104
	v_fmac_f32_e32 v105, v80, v92
	v_mul_f32_e32 v106, v105, v100
	v_fma_f32 v106, v104, v96, -v106
	v_add_f32_e32 v18, v18, v106
	v_mul_f32_e32 v104, v85, v93
	v_mul_f32_e32 v105, v85, v89
	v_fma_f32 v104, v81, v89, -v104
	v_fmac_f32_e32 v105, v81, v93
	v_mul_f32_e32 v106, v105, v101
	v_fma_f32 v106, v104, v97, -v106
	v_add_f32_e32 v18, v18, v106
	v_mul_f32_e32 v104, v86, v94
	v_mul_f32_e32 v105, v86, v90
	v_fma_f32 v104, v82, v90, -v104
	v_fmac_f32_e32 v105, v82, v94
	v_mul_f32_e32 v106, v105, v102
	v_fma_f32 v106, v104, v98, -v106
	v_add_f32_e32 v18, v18, v106
	v_mul_f32_e32 v104, v87, v95
	v_mul_f32_e32 v105, v87, v91
	v_fma_f32 v104, v83, v91, -v104
	v_fmac_f32_e32 v105, v83, v95
	v_mul_f32_e32 v106, v105, v103
	v_fma_f32 v106, v104, v99, -v106
	v_add_f32_e32 v18, v18, v106
	v_add_u32_e32 v107, 0xa00, v19
	v_add_u32_e32 v108, 0x1a00, v19
	ds_read_b128 v[80:83], v16 offset:160
	ds_read_b128 v[84:87], v16 offset:4256
	ds_read_b128 v[88:91], v17 offset:160
	ds_read_b128 v[92:95], v17 offset:2464
	ds_read2_b32 v[96:97], v107 offset1:16
	ds_read2_b32 v[98:99], v107 offset0:32 offset1:48
	ds_read2_b32 v[100:101], v108 offset1:16
	ds_read2_b32 v[102:103], v108 offset0:32 offset1:48
	s_waitcnt lgkmcnt(8)
	v_mul_f32_e32 v104, v134, v142
	v_mul_f32_e32 v105, v134, v138
	v_fma_f32 v104, v130, v138, -v104
	v_fmac_f32_e32 v105, v130, v142
	v_mul_f32_e32 v106, v105, v150
	v_fma_f32 v106, v104, v146, -v106
	v_add_f32_e32 v18, v18, v106
	v_mul_f32_e32 v104, v135, v143
	v_mul_f32_e32 v105, v135, v139
	v_fma_f32 v104, v131, v139, -v104
	v_fmac_f32_e32 v105, v131, v143
	v_mul_f32_e32 v106, v105, v151
	v_fma_f32 v106, v104, v147, -v106
	v_add_f32_e32 v18, v18, v106
	v_mul_f32_e32 v104, v136, v144
	v_mul_f32_e32 v105, v136, v140
	v_fma_f32 v104, v132, v140, -v104
	v_fmac_f32_e32 v105, v132, v144
	v_mul_f32_e32 v106, v105, v152
	v_fma_f32 v106, v104, v148, -v106
	v_add_f32_e32 v18, v18, v106
	v_mul_f32_e32 v104, v137, v145
	v_mul_f32_e32 v105, v137, v141
	v_fma_f32 v104, v133, v141, -v104
	v_fmac_f32_e32 v105, v133, v145
	v_mul_f32_e32 v106, v105, v153
	v_fma_f32 v106, v104, v149, -v106
	v_add_f32_e32 v18, v18, v106
	v_add_u32_e32 v107, 0xb00, v19
	v_add_u32_e32 v108, 0x1b00, v19
	ds_read_b128 v[130:133], v16 offset:176
	ds_read_b128 v[134:137], v16 offset:4272
	ds_read_b128 v[138:141], v17 offset:176
	ds_read_b128 v[142:145], v17 offset:2480
	ds_read2_b32 v[146:147], v107 offset1:16
	ds_read2_b32 v[148:149], v107 offset0:32 offset1:48
	ds_read2_b32 v[150:151], v108 offset1:16
	ds_read2_b32 v[152:153], v108 offset0:32 offset1:48
	s_waitcnt lgkmcnt(8)
	v_mul_f32_e32 v104, v84, v92
	v_mul_f32_e32 v105, v84, v88
	v_fma_f32 v104, v80, v88, -v104
	v_fmac_f32_e32 v105, v80, v92
	v_mul_f32_e32 v106, v105, v100
	v_fma_f32 v106, v104, v96, -v106
	v_add_f32_e32 v18, v18, v106
	v_mul_f32_e32 v104, v85, v93
	v_mul_f32_e32 v105, v85, v89
	v_fma_f32 v104, v81, v89, -v104
	v_fmac_f32_e32 v105, v81, v93
	v_mul_f32_e32 v106, v105, v101
	v_fma_f32 v106, v104, v97, -v106
	v_add_f32_e32 v18, v18, v106
	v_mul_f32_e32 v104, v86, v94
	v_mul_f32_e32 v105, v86, v90
	v_fma_f32 v104, v82, v90, -v104
	v_fmac_f32_e32 v105, v82, v94
	v_mul_f32_e32 v106, v105, v102
	v_fma_f32 v106, v104, v98, -v106
	v_add_f32_e32 v18, v18, v106
	v_mul_f32_e32 v104, v87, v95
	v_mul_f32_e32 v105, v87, v91
	v_fma_f32 v104, v83, v91, -v104
	v_fmac_f32_e32 v105, v83, v95
	v_mul_f32_e32 v106, v105, v103
	v_fma_f32 v106, v104, v99, -v106
	v_add_f32_e32 v18, v18, v106
	v_add_u32_e32 v107, 0xc00, v19
	v_add_u32_e32 v108, 0x1c00, v19
	ds_read_b128 v[80:83], v16 offset:192
	ds_read_b128 v[84:87], v16 offset:4288
	ds_read_b128 v[88:91], v17 offset:192
	ds_read_b128 v[92:95], v17 offset:2496
	ds_read2_b32 v[96:97], v107 offset1:16
	ds_read2_b32 v[98:99], v107 offset0:32 offset1:48
	ds_read2_b32 v[100:101], v108 offset1:16
	ds_read2_b32 v[102:103], v108 offset0:32 offset1:48
	s_waitcnt lgkmcnt(8)
	v_mul_f32_e32 v104, v134, v142
	v_mul_f32_e32 v105, v134, v138
	v_fma_f32 v104, v130, v138, -v104
	v_fmac_f32_e32 v105, v130, v142
	v_mul_f32_e32 v106, v105, v150
	v_fma_f32 v106, v104, v146, -v106
	v_add_f32_e32 v18, v18, v106
	v_mul_f32_e32 v104, v135, v143
	v_mul_f32_e32 v105, v135, v139
	v_fma_f32 v104, v131, v139, -v104
	v_fmac_f32_e32 v105, v131, v143
	v_mul_f32_e32 v106, v105, v151
	v_fma_f32 v106, v104, v147, -v106
	v_add_f32_e32 v18, v18, v106
	v_mul_f32_e32 v104, v136, v144
	v_mul_f32_e32 v105, v136, v140
	v_fma_f32 v104, v132, v140, -v104
	v_fmac_f32_e32 v105, v132, v144
	v_mul_f32_e32 v106, v105, v152
	v_fma_f32 v106, v104, v148, -v106
	v_add_f32_e32 v18, v18, v106
	v_mul_f32_e32 v104, v137, v145
	v_mul_f32_e32 v105, v137, v141
	v_fma_f32 v104, v133, v141, -v104
	v_fmac_f32_e32 v105, v133, v145
	v_mul_f32_e32 v106, v105, v153
	v_fma_f32 v106, v104, v149, -v106
	v_add_f32_e32 v18, v18, v106
	v_add_u32_e32 v107, 0xd00, v19
	v_add_u32_e32 v108, 0x1d00, v19
	ds_read_b128 v[130:133], v16 offset:208
	ds_read_b128 v[134:137], v16 offset:4304
	ds_read_b128 v[138:141], v17 offset:208
	ds_read_b128 v[142:145], v17 offset:2512
	ds_read2_b32 v[146:147], v107 offset1:16
	ds_read2_b32 v[148:149], v107 offset0:32 offset1:48
	ds_read2_b32 v[150:151], v108 offset1:16
	ds_read2_b32 v[152:153], v108 offset0:32 offset1:48
	s_waitcnt lgkmcnt(8)
; __device__ __forceinline__ void ssm_tables(const Params& p, int g, int part, LAS float* sm, int tid) {
;     ...
;         for (int e = tid; e < 2048; e += 512) { const int l = e >> 8, pch = (e >> 4) & 15, q = e & 15; float s = 0.f;
;             for (int n = 0; n < 64; ++n) { const float cr = cre[pch * 64 + n], ci = cim[pch * 64 + n], ar = pwr[l * 64 + n], ai = pwi[l * 64 + n];
;                 const float zr = cr * ar - ci * ai, zi = cr * ai + ci * ar; s += zr * bbr[n * 16 + q] - zi * bbi[n * 16 + q]; }
;             kc[e] = s; }
	v_mul_f32_e32 v104, v84, v92
	v_mul_f32_e32 v105, v84, v88
	v_fma_f32 v104, v80, v88, -v104
	v_fmac_f32_e32 v105, v80, v92
	v_mul_f32_e32 v106, v105, v100
	v_fma_f32 v106, v104, v96, -v106
	v_add_f32_e32 v18, v18, v106
	v_mul_f32_e32 v104, v85, v93
	v_mul_f32_e32 v105, v85, v89
	v_fma_f32 v104, v81, v89, -v104
	v_fmac_f32_e32 v105, v81, v93
	v_mul_f32_e32 v106, v105, v101
	v_fma_f32 v106, v104, v97, -v106
	v_add_f32_e32 v18, v18, v106
	v_mul_f32_e32 v104, v86, v94
	v_mul_f32_e32 v105, v86, v90
	v_fma_f32 v104, v82, v90, -v104
	v_fmac_f32_e32 v105, v82, v94
	v_mul_f32_e32 v106, v105, v102
	v_fma_f32 v106, v104, v98, -v106
	v_add_f32_e32 v18, v18, v106
	v_mul_f32_e32 v104, v87, v95
	v_mul_f32_e32 v105, v87, v91
	v_fma_f32 v104, v83, v91, -v104
	v_fmac_f32_e32 v105, v83, v95
	v_mul_f32_e32 v106, v105, v103
	v_fma_f32 v106, v104, v99, -v106
	v_add_f32_e32 v18, v18, v106
	v_add_u32_e32 v107, 0xe00, v19
	v_add_u32_e32 v108, 0x1e00, v19
	ds_read_b128 v[80:83], v16 offset:224
	ds_read_b128 v[84:87], v16 offset:4320
	ds_read_b128 v[88:91], v17 offset:224
	ds_read_b128 v[92:95], v17 offset:2528
	ds_read2_b32 v[96:97], v107 offset1:16
	ds_read2_b32 v[98:99], v107 offset0:32 offset1:48
	ds_read2_b32 v[100:101], v108 offset1:16
	ds_read2_b32 v[102:103], v108 offset0:32 offset1:48
	s_waitcnt lgkmcnt(8)
	v_mul_f32_e32 v104, v134, v142
	v_mul_f32_e32 v105, v134, v138
	v_fma_f32 v104, v130, v138, -v104
	v_fmac_f32_e32 v105, v130, v142
	v_mul_f32_e32 v106, v105, v150
	v_fma_f32 v106, v104, v146, -v106
	v_add_f32_e32 v18, v18, v106
	v_mul_f32_e32 v104, v135, v143
	v_mul_f32_e32 v105, v135, v139
	v_fma_f32 v104, v131, v139, -v104
	v_fmac_f32_e32 v105, v131, v143
	v_mul_f32_e32 v106, v105, v151
	v_fma_f32 v106, v104, v147, -v106
	v_add_f32_e32 v18, v18, v106
	v_mul_f32_e32 v104, v136, v144
	v_mul_f32_e32 v105, v136, v140
	v_fma_f32 v104, v132, v140, -v104
	v_fmac_f32_e32 v105, v132, v144
	v_mul_f32_e32 v106, v105, v152
	v_fma_f32 v106, v104, v148, -v106
	v_add_f32_e32 v18, v18, v106
	v_mul_f32_e32 v104, v137, v145
	v_mul_f32_e32 v105, v137, v141
	v_fma_f32 v104, v133, v141, -v104
	v_fmac_f32_e32 v105, v133, v145
	v_mul_f32_e32 v106, v105, v153
	v_fma_f32 v106, v104, v149, -v106
	v_add_f32_e32 v18, v18, v106
	v_add_u32_e32 v107, 0xf00, v19
	v_add_u32_e32 v108, 0x1f00, v19
	ds_read_b128 v[130:133], v16 offset:240
	ds_read_b128 v[134:137], v16 offset:4336
	ds_read_b128 v[138:141], v17 offset:240
	ds_read_b128 v[142:145], v17 offset:2544
	ds_read2_b32 v[146:147], v107 offset1:16
	ds_read2_b32 v[148:149], v107 offset0:32 offset1:48
	ds_read2_b32 v[150:151], v108 offset1:16
	ds_read2_b32 v[152:153], v108 offset0:32 offset1:48
	s_waitcnt lgkmcnt(8)
	v_mul_f32_e32 v104, v84, v92
	v_mul_f32_e32 v105, v84, v88
	v_fma_f32 v104, v80, v88, -v104
	v_fmac_f32_e32 v105, v80, v92
	v_mul_f32_e32 v106, v105, v100
	v_fma_f32 v106, v104, v96, -v106
	v_add_f32_e32 v18, v18, v106
	v_mul_f32_e32 v104, v85, v93
	v_mul_f32_e32 v105, v85, v89
	v_fma_f32 v104, v81, v89, -v104
	v_fmac_f32_e32 v105, v81, v93
	v_mul_f32_e32 v106, v105, v101
	v_fma_f32 v106, v104, v97, -v106
	v_add_f32_e32 v18, v18, v106
	v_mul_f32_e32 v104, v86, v94
	v_mul_f32_e32 v105, v86, v90
	v_fma_f32 v104, v82, v90, -v104
	v_fmac_f32_e32 v105, v82, v94
	v_mul_f32_e32 v106, v105, v102
	v_fma_f32 v106, v104, v98, -v106
	v_add_f32_e32 v18, v18, v106
	v_mul_f32_e32 v104, v87, v95
	v_mul_f32_e32 v105, v87, v91
	v_fma_f32 v104, v83, v91, -v104
	v_fmac_f32_e32 v105, v83, v95
	v_mul_f32_e32 v106, v105, v103
	v_fma_f32 v106, v104, v99, -v106
	v_add_f32_e32 v18, v18, v106
	s_waitcnt lgkmcnt(0)
	v_mul_f32_e32 v104, v134, v142
	v_mul_f32_e32 v105, v134, v138
	v_fma_f32 v104, v130, v138, -v104
	v_fmac_f32_e32 v105, v130, v142
	v_mul_f32_e32 v106, v105, v150
	v_fma_f32 v106, v104, v146, -v106
	v_add_f32_e32 v18, v18, v106
	v_mul_f32_e32 v104, v135, v143
	v_mul_f32_e32 v105, v135, v139
	v_fma_f32 v104, v131, v139, -v104
	v_fmac_f32_e32 v105, v131, v143
	v_mul_f32_e32 v106, v105, v151
	v_fma_f32 v106, v104, v147, -v106
	v_add_f32_e32 v18, v18, v106
	v_mul_f32_e32 v104, v136, v144
	v_mul_f32_e32 v105, v136, v140
	v_fma_f32 v104, v132, v140, -v104
	v_fmac_f32_e32 v105, v132, v144
	v_mul_f32_e32 v106, v105, v152
	v_fma_f32 v106, v104, v148, -v106
	v_add_f32_e32 v18, v18, v106
	v_mul_f32_e32 v104, v137, v145
	v_mul_f32_e32 v105, v137, v141
	v_fma_f32 v104, v133, v141, -v104
	v_fmac_f32_e32 v105, v133, v145
	v_mul_f32_e32 v106, v105, v153
	v_fma_f32 v106, v104, v149, -v106
	v_add_f32_e32 v18, v18, v106
	v_lshl_add_u32 v16, v14, 2, 0
	ds_write_b32 v16, v18 offset:21504
	v_add_u32_e32 v16, 0x200, v14
	v_cmp_lt_i32_e32 vcc, s30, v14
	v_add_u32_e32 v9, 0x800, v9
	s_or_b64 s[22:23], vcc, s[22:23]
	v_mov_b32_e32 v14, v16
	s_andn2_b64 exec, exec, s[22:23]
	s_cbranch_execnz .LBB0_235

; #define LAS __attribute__((address_space(3)))
;     __device__ __forceinline__ void piece(size_t row, int col, f32x4 v0, f32x4 v1, const f32x4 a0, const f32x4 a1, const f32x4 b0, const f32x4 b1, const f32x4 c0, const f32x4 c1,
;                                           float mean, float rstd, float& s, float& ss) const {
;         if constexpr (MODE == 1) { f32x4 r0, r1; unpack8(*(const u32x4*)(Tin + row * DM + col), r0, r1); v0 = r0 * ALPHA + v0; v1 = r1 * ALPHA + v1; }
;         if constexpr (MODE == 2) { v0 = ((v0 - a0 * mean) * rstd + b0) * scale; v1 = ((v1 - a1 * mean) * rstd + b1) * scale; }
;         if constexpr (RECOMP) { f32x4 r0, r1; unpack8(*(const u32x4*)(Tin + row * DM + col), r0, r1);
;     __device__ __forceinline__ void operator()(const f32x4 (&acc)[2][2][4][2], const Unit& u, int wr, int wc, int fr_, int fq_, LAS unsigned char* ldsx) const {
;         int fr = fr_, fq = fq_; asm volatile("" : "+v"(fr), "+v"(fq));
;         LAS f32x2* X = (LAS f32x2*)ldsx;
;         X += (u.row0 == tag0) ? 0 : 256;
;         const int colb = u.col0 + wc * 32 + 8 * fq;
;         const f32x4 z = (f32x4){0.f, 0.f, 0.f, 0.f};
;         f32x4 av[2][2], bv[2][2], cv[2][2];
; #pragma unroll
;         for (int bj = 0; bj < 2; ++bj)
; #pragma unroll
;             for (int n = 0; n < 2; ++n) { av[bj][n] = CONS ? *(const f32x4*)(va + colb + bj * HALF + 4 * n) : z; bv[bj][n] = CONS ? *(const f32x4*)(vb + colb + bj * HALF + 4 * n) : z;
;                                           cv[bj][n] = (MODE == 5) ? *(const f32x4*)(bias + colb + bj * HALF + 4 * n) : z; }
; #pragma unroll
;         EPI_FOR_ROWS {
;             const int rl = ai * HALF + wr * 64 + m * 16 + fr; const size_t row = (size_t)u.row0 + rl;
;             float mean = 0.f, rstd = 0.f; if constexpr (CONS) { const f32x2 st = X[rl]; mean = st.x; rstd = st.y; }
;             float s = 0.f, ss = 0.f;
; #pragma unroll
;             for (int bj = 0; bj < 2; ++bj) piece(row, colb + bj * HALF, acc[ai][bj][m][0], acc[ai][bj][m][1], av[bj][0], av[bj][1], bv[bj][0], bv[bj][1], cv[bj][0], cv[bj][1], mean, rstd, s, ss);
;             if constexpr (PROD) { s += __shfl_xor(s, 16); ss += __shfl_xor(ss, 16); s += __shfl_xor(s, 32); ss += __shfl_xor(ss, 32);
;                 if (fq == 0) st_out[row * 16 + (u.col0 >> 8) * 4 + wc] = (f32x2){s, ss}; }
;         }
.LBB0_1480:
	v_mov_b32_e32 v82, v204
	v_mov_b32_e32 v80, v205
	s_cmp_eq_u32 s20, s8
	s_cselect_b32 s23, 0, 0x800
	s_add_i32 s21, s30, s43
	v_add_u32_e32 v198, s42, v82
	v_lshl_add_u32 v80, v80, 3, s21
	s_ashr_i32 s21, s20, 31
	v_ashrrev_i32_e32 v199, 31, v198
	v_lshl_add_u64 v[82:83], v[198:199], 0, s[20:21]
	v_ashrrev_i32_e32 v81, 31, v80
	v_lshlrev_b64 v[84:85], 11, v[82:83]
	v_lshl_add_u64 v[84:85], s[88:89], 0, v[84:85]
	v_lshlrev_b64 v[200:201], 1, v[80:81]
	v_lshl_add_u64 v[214:215], v[84:85], 0, v[200:201]
	v_readlane_b32 s64, v254, 3
	global_load_dwordx4 v[210:213], v[214:215], off
	v_readlane_b32 s76, v254, 15
	v_readlane_b32 s77, v254, 16
	v_readlane_b32 s78, v254, 17
	v_readlane_b32 s79, v254, 18
	s_mov_b64 s[16:17], s[76:77]
	v_lshlrev_b64 v[196:197], 2, v[80:81]
	s_mov_b64 s[18:19], s[78:79]
	v_lshl_add_u64 v[84:85], s[18:19], 0, v[196:197]
	v_lshl_add_u64 v[80:81], s[16:17], 0, v[196:197]
	global_load_dwordx4 v[116:119], v[84:85], off
	global_load_dwordx4 v[120:123], v[80:81], off
	global_load_dwordx4 v[112:115], v[80:81], off offset:16
	global_load_dwordx4 v[124:127], v[84:85], off offset:16
	v_lshl_add_u64 v[86:87], s[50:51], 0, v[196:197]
	global_load_dwordx4 v[108:111], v[86:87], off
	global_load_dwordx4 v[104:107], v[86:87], off offset:16
	s_add_i32 s23, s23, 0
	v_lshl_add_u32 v88, v198, 3, s23
	v_add_u32_e32 v199, 0x20000, v88
	ds_read2_b64 v[176:179], v199 offset1:16
	v_lshlrev_b64 v[216:217], 12, v[82:83]
	v_lshl_add_u64 v[216:217], s[56:57], 0, v[216:217]
	v_lshl_add_u64 v[216:217], v[216:217], 0, v[196:197]
	global_load_dwordx4 v[88:91], v[80:81], off offset:528
	global_load_dwordx4 v[96:99], v[80:81], off offset:512
	global_load_dwordx4 v[92:95], v[84:85], off offset:528
	global_load_dwordx4 v[100:103], v[84:85], off offset:512
	s_nop 0
	global_load_dwordx4 v[80:83], v[86:87], off offset:528
	s_nop 0
	global_load_dwordx4 v[84:87], v[86:87], off offset:512
	s_andn2_b64 vcc, exec, s[0:1]
	s_mov_b64 s[0:1], -1
	v_readlane_b32 s65, v254, 4
	v_readlane_b32 s66, v254, 5
	v_readlane_b32 s67, v254, 6
	v_readlane_b32 s68, v254, 7
	v_readlane_b32 s69, v254, 8
	v_readlane_b32 s70, v254, 9
	v_readlane_b32 s71, v254, 10
	v_readlane_b32 s72, v254, 11
	v_readlane_b32 s73, v254, 12
	v_readlane_b32 s74, v254, 13
	v_readlane_b32 s75, v254, 14
	global_load_dwordx4 v[218:221], v[214:215], off offset:256
	v_add_u32_e32 v250, 0x10, v198
	v_ashrrev_i32_e32 v251, 31, v250
	v_lshl_add_u64 v[250:251], v[250:251], 0, s[20:21]
	v_lshlrev_b64 v[250:251], 11, v[250:251]
	v_lshl_add_u64 v[250:251], s[88:89], 0, v[250:251]
	v_lshl_add_u64 v[250:251], v[250:251], 0, v[200:201]
	global_load_dwordx4 v[222:225], v[250:251], off
	v_add_u32_e32 v250, 0x10, v198
	v_ashrrev_i32_e32 v251, 31, v250
	v_lshl_add_u64 v[250:251], v[250:251], 0, s[20:21]
	v_lshlrev_b64 v[250:251], 11, v[250:251]
	v_lshl_add_u64 v[250:251], s[88:89], 0, v[250:251]
	v_lshl_add_u64 v[250:251], v[250:251], 0, v[200:201]
	global_load_dwordx4 v[226:229], v[250:251], off offset:256
	v_add_u32_e32 v250, 0x20, v198
	v_ashrrev_i32_e32 v251, 31, v250
	v_lshl_add_u64 v[250:251], v[250:251], 0, s[20:21]
	v_lshlrev_b64 v[250:251], 11, v[250:251]
	v_lshl_add_u64 v[250:251], s[88:89], 0, v[250:251]
	v_lshl_add_u64 v[250:251], v[250:251], 0, v[200:201]
	global_load_dwordx4 v[230:233], v[250:251], off
	v_add_u32_e32 v250, 0x20, v198
	v_ashrrev_i32_e32 v251, 31, v250
	v_lshl_add_u64 v[250:251], v[250:251], 0, s[20:21]
	v_lshlrev_b64 v[250:251], 11, v[250:251]
	v_lshl_add_u64 v[250:251], s[88:89], 0, v[250:251]
	v_lshl_add_u64 v[250:251], v[250:251], 0, v[200:201]
	global_load_dwordx4 v[234:237], v[250:251], off offset:256
	ds_read2_b64 v[238:241], v199 offset0:32 offset1:48
	ds_read2_b64 v[242:245], v199 offset0:128 offset1:144
	ds_read2_b64 v[246:249], v199 offset0:160 offset1:176
	s_waitcnt vmcnt(5)
	v_pk_mul_f32 v[120:121], v[120:121], s[14:15] op_sel_hi:[1,0]
	v_pk_fma_f32 v[116:117], v[116:117], s[14:15], v[108:109] op_sel_hi:[1,0,1]
	v_pk_mul_f32 v[122:123], v[122:123], s[14:15] op_sel_hi:[1,0]
	v_pk_fma_f32 v[118:119], v[118:119], s[14:15], v[110:111] op_sel_hi:[1,0,1]
	v_pk_mul_f32 v[112:113], v[112:113], s[14:15] op_sel_hi:[1,0]
	v_pk_fma_f32 v[124:125], v[124:125], s[14:15], v[104:105] op_sel_hi:[1,0,1]
	v_pk_mul_f32 v[114:115], v[114:115], s[14:15] op_sel_hi:[1,0]
	v_pk_fma_f32 v[126:127], v[126:127], s[14:15], v[106:107] op_sel_hi:[1,0,1]
	v_pk_mul_f32 v[96:97], v[96:97], s[14:15] op_sel_hi:[1,0]
	v_pk_fma_f32 v[100:101], v[100:101], s[14:15], v[84:85] op_sel_hi:[1,0,1]
	v_pk_mul_f32 v[98:99], v[98:99], s[14:15] op_sel_hi:[1,0]
	v_pk_fma_f32 v[102:103], v[102:103], s[14:15], v[86:87] op_sel_hi:[1,0,1]
	v_pk_mul_f32 v[88:89], v[88:89], s[14:15] op_sel_hi:[1,0]
	v_pk_fma_f32 v[92:93], v[92:93], s[14:15], v[80:81] op_sel_hi:[1,0,1]
	v_pk_mul_f32 v[90:91], v[90:91], s[14:15] op_sel_hi:[1,0]
	v_pk_fma_f32 v[94:95], v[94:95], s[14:15], v[82:83] op_sel_hi:[1,0,1]
	v_mbcnt_lo_u32_b32 v110, -1, 0
	v_mbcnt_hi_u32_b32 v110, -1, v110
	v_xor_b32_e32 v111, 32, v110
	v_xor_b32_e32 v110, 16, v110
	v_lshlrev_b32_e32 v111, 2, v111
	v_lshlrev_b32_e32 v110, 2, v110
	v_lshlrev_b32_e32 v252, 5, v198
	v_mov_b32_e32 v108, s43
	v_lshrrev_b32_e32 v108, 2, v108
	v_add_u32_e32 v252, v252, v108
	v_add_u32_e32 v252, 0x21000, v252
	s_waitcnt lgkmcnt(0)
	s_waitcnt vmcnt(5)
; #define EPI_FOR_ROWS for (int ai = 0; ai < 2; ++ai) _Pragma("unroll") for (int m = 0; m < 4; ++m)
; __device__ __forceinline__ void unpack8(const u32x4 w, f32x4& a, f32x4& b) { a = (f32x4){bf_lo(w.x), bf_hi(w.x), bf_lo(w.y), bf_hi(w.y)}; b = (f32x4){bf_lo(w.z), bf_hi(w.z), bf_lo(w.w), bf_hi(w.w)}; }
;     __device__ __forceinline__ void piece(size_t row, int col, f32x4 v0, f32x4 v1, const f32x4 a0, const f32x4 a1, const f32x4 b0, const f32x4 b1, const f32x4 c0, const f32x4 c1,
;                                           float mean, float rstd, float& s, float& ss) const {
;     ...
;         if constexpr (RECOMP) { f32x4 r0, r1; unpack8(*(const u32x4*)(Tin + row * DM + col), r0, r1);
;             r0 = (r0 - mean) * rstd * a0 + b0; r1 = (r1 - mean) * rstd * a1 + b1; v0 = r0 * ALPHA + v0; v1 = r1 * ALPHA + v1;
;             if constexpr (MODE == 5) { v0 = v0 + c0; v1 = v1 + c1; } }
;         if constexpr (MODE == 4) { v0 = (v0 - a0 * mean) * rstd + b0; v1 = (v1 - a1 * mean) * rstd + b1;
; #pragma unroll
;             for (int e = 0; e < 4; ++e) { const float x = fmaxf(v0[e], 0.f), y = fmaxf(v1[e], 0.f); v0[e] = x * x; v1[e] = y * y; } }
;         if constexpr (PROD) {
; #pragma unroll
;             for (int e = 0; e < 4; ++e) { s += v0[e] + v1[e]; ss += v0[e] * v0[e] + v1[e] * v1[e]; } }
;     __device__ __forceinline__ void operator()(const f32x4 (&acc)[2][2][4][2], const Unit& u, int wr, int wc, int fr_, int fq_, LAS unsigned char* ldsx) const {
;     ...
;         EPI_FOR_ROWS {
;             const int rl = ai * HALF + wr * 64 + m * 16 + fr; const size_t row = (size_t)u.row0 + rl;
;             float mean = 0.f, rstd = 0.f; if constexpr (CONS) { const f32x2 st = X[rl]; mean = st.x; rstd = st.y; }
;             float s = 0.f, ss = 0.f;
; #pragma unroll
;             for (int bj = 0; bj < 2; ++bj) piece(row, colb + bj * HALF, acc[ai][bj][m][0], acc[ai][bj][m][1], av[bj][0], av[bj][1], bv[bj][0], bv[bj][1], cv[bj][0], cv[bj][1], mean, rstd, s, ss);
;             if constexpr (PROD) { s += __shfl_xor(s, 16); ss += __shfl_xor(ss, 16); s += __shfl_xor(s, 32); ss += __shfl_xor(ss, 32);
;                 if (fq == 0) st_out[row * 16 + (u.col0 >> 8) * 4 + wc] = (f32x2){s, ss}; }
;         }
	v_lshlrev_b32_e32 v80, 16, v210
	v_and_b32_e32 v81, 0xffff0000, v210
	v_lshlrev_b32_e32 v82, 16, v211
	v_and_b32_e32 v83, 0xffff0000, v211
	v_lshlrev_b32_e32 v84, 16, v212
	v_and_b32_e32 v85, 0xffff0000, v212
	v_lshlrev_b32_e32 v86, 16, v213
	v_and_b32_e32 v87, 0xffff0000, v213
	v_add_u32_e32 v250, 0x30, v198
	v_ashrrev_i32_e32 v251, 31, v250
	v_lshl_add_u64 v[250:251], v[250:251], 0, s[20:21]
	v_lshlrev_b64 v[250:251], 11, v[250:251]
	v_lshl_add_u64 v[250:251], s[88:89], 0, v[250:251]
	v_lshl_add_u64 v[250:251], v[250:251], 0, v[200:201]
	global_load_dwordx4 v[210:213], v[250:251], off
	v_pk_add_f32 v[80:81], v[80:81], v[176:177] op_sel_hi:[1,0] neg_lo:[0,1] neg_hi:[0,1]
	v_pk_mul_f32 v[80:81], v[176:177], v[80:81] op_sel:[1,0]
	v_pk_fma_f32 v[80:81], v[80:81], v[120:121], v[116:117]
	v_pk_add_f32 v[172:173], v[172:173], v[80:81]
	v_pk_add_f32 v[82:83], v[82:83], v[176:177] op_sel_hi:[1,0] neg_lo:[0,1] neg_hi:[0,1]
	v_pk_mul_f32 v[82:83], v[176:177], v[82:83] op_sel:[1,0]
	v_pk_fma_f32 v[82:83], v[82:83], v[122:123], v[118:119]
	v_pk_add_f32 v[174:175], v[174:175], v[82:83]
	v_pk_add_f32 v[84:85], v[84:85], v[176:177] op_sel_hi:[1,0] neg_lo:[0,1] neg_hi:[0,1]
	v_pk_mul_f32 v[84:85], v[176:177], v[84:85] op_sel:[1,0]
	v_pk_fma_f32 v[84:85], v[84:85], v[112:113], v[124:125]
	v_pk_add_f32 v[168:169], v[168:169], v[84:85]
	v_pk_add_f32 v[86:87], v[86:87], v[176:177] op_sel_hi:[1,0] neg_lo:[0,1] neg_hi:[0,1]
	v_pk_mul_f32 v[86:87], v[176:177], v[86:87] op_sel:[1,0]
	v_pk_fma_f32 v[86:87], v[86:87], v[114:115], v[126:127]
	v_pk_add_f32 v[170:171], v[170:171], v[86:87]
	v_pk_mul_f32 v[106:107], v[172:173], v[172:173]
	v_pk_add_f32 v[104:105], v[172:173], v[174:175]
	v_pk_fma_f32 v[106:107], v[174:175], v[174:175], v[106:107]
	v_pk_add_f32 v[104:105], v[104:105], v[168:169]
	v_pk_fma_f32 v[106:107], v[168:169], v[168:169], v[106:107]
	v_pk_add_f32 v[104:105], v[104:105], v[170:171]
	v_pk_fma_f32 v[106:107], v[170:171], v[170:171], v[106:107]
	s_waitcnt vmcnt(5)
	v_lshlrev_b32_e32 v80, 16, v218
	v_and_b32_e32 v81, 0xffff0000, v218
	v_lshlrev_b32_e32 v82, 16, v219
	v_and_b32_e32 v83, 0xffff0000, v219
	v_lshlrev_b32_e32 v84, 16, v220
	v_and_b32_e32 v85, 0xffff0000, v220
	v_lshlrev_b32_e32 v86, 16, v221
	v_and_b32_e32 v87, 0xffff0000, v221
	v_add_u32_e32 v250, 0x30, v198
	v_ashrrev_i32_e32 v251, 31, v250
	v_lshl_add_u64 v[250:251], v[250:251], 0, s[20:21]
	v_lshlrev_b64 v[250:251], 11, v[250:251]
	v_lshl_add_u64 v[250:251], s[88:89], 0, v[250:251]
	v_lshl_add_u64 v[250:251], v[250:251], 0, v[200:201]
	global_load_dwordx4 v[218:221], v[250:251], off offset:256
	v_pk_add_f32 v[80:81], v[80:81], v[176:177] op_sel_hi:[1,0] neg_lo:[0,1] neg_hi:[0,1]
	v_pk_mul_f32 v[80:81], v[176:177], v[80:81] op_sel:[1,0]
	v_pk_fma_f32 v[80:81], v[80:81], v[96:97], v[100:101]
	v_pk_add_f32 v[164:165], v[164:165], v[80:81]
	v_pk_add_f32 v[82:83], v[82:83], v[176:177] op_sel_hi:[1,0] neg_lo:[0,1] neg_hi:[0,1]
	v_pk_mul_f32 v[82:83], v[176:177], v[82:83] op_sel:[1,0]
	v_pk_fma_f32 v[82:83], v[82:83], v[98:99], v[102:103]
	v_pk_add_f32 v[166:167], v[166:167], v[82:83]
	v_pk_add_f32 v[84:85], v[84:85], v[176:177] op_sel_hi:[1,0] neg_lo:[0,1] neg_hi:[0,1]
	v_pk_mul_f32 v[84:85], v[176:177], v[84:85] op_sel:[1,0]
	v_pk_fma_f32 v[84:85], v[84:85], v[88:89], v[92:93]
	v_pk_add_f32 v[160:161], v[160:161], v[84:85]
	v_pk_add_f32 v[86:87], v[86:87], v[176:177] op_sel_hi:[1,0] neg_lo:[0,1] neg_hi:[0,1]
	v_pk_mul_f32 v[86:87], v[176:177], v[86:87] op_sel:[1,0]
	v_pk_fma_f32 v[86:87], v[86:87], v[90:91], v[94:95]
	v_pk_add_f32 v[162:163], v[162:163], v[86:87]
	v_pk_add_f32 v[104:105], v[104:105], v[164:165]
	v_pk_fma_f32 v[106:107], v[164:165], v[164:165], v[106:107]
	v_pk_add_f32 v[104:105], v[104:105], v[166:167]
	v_pk_fma_f32 v[106:107], v[166:167], v[166:167], v[106:107]
	v_pk_add_f32 v[104:105], v[104:105], v[160:161]
	v_pk_fma_f32 v[106:107], v[160:161], v[160:161], v[106:107]
	v_pk_add_f32 v[104:105], v[104:105], v[162:163]
	v_pk_fma_f32 v[106:107], v[162:163], v[162:163], v[106:107]
	v_add_f32_e32 v108, v104, v105
	v_add_f32_e32 v109, v106, v107
	s_nop 0
	ds_bpermute_b32 v104, v110, v108
	ds_bpermute_b32 v105, v110, v109
	s_waitcnt lgkmcnt(0)
	v_pk_add_f32 v[108:109], v[108:109], v[104:105]
	s_nop 0
	ds_bpermute_b32 v104, v111, v108
	ds_bpermute_b32 v105, v111, v109
	s_waitcnt lgkmcnt(0)
	v_pk_add_f32 v[108:109], v[108:109], v[104:105]
	ds_write_b64 v252, v[108:109] offset:0
	s_waitcnt vmcnt(5)
	v_lshlrev_b32_e32 v80, 16, v222
	v_and_b32_e32 v81, 0xffff0000, v222
	v_lshlrev_b32_e32 v82, 16, v223
	v_and_b32_e32 v83, 0xffff0000, v223
	v_lshlrev_b32_e32 v84, 16, v224
	v_and_b32_e32 v85, 0xffff0000, v224
	v_lshlrev_b32_e32 v86, 16, v225
	v_and_b32_e32 v87, 0xffff0000, v225
	v_add_u32_e32 v250, 0x80, v198
	v_ashrrev_i32_e32 v251, 31, v250
	v_lshl_add_u64 v[250:251], v[250:251], 0, s[20:21]
	v_lshlrev_b64 v[250:251], 11, v[250:251]
	v_lshl_add_u64 v[250:251], s[88:89], 0, v[250:251]
	v_lshl_add_u64 v[250:251], v[250:251], 0, v[200:201]
	global_load_dwordx4 v[222:225], v[250:251], off
	v_pk_add_f32 v[80:81], v[80:81], v[178:179] op_sel_hi:[1,0] neg_lo:[0,1] neg_hi:[0,1]
	v_pk_mul_f32 v[80:81], v[178:179], v[80:81] op_sel:[1,0]
	v_pk_fma_f32 v[80:81], v[80:81], v[120:121], v[116:117]
	v_pk_add_f32 v[156:157], v[156:157], v[80:81]
	v_pk_add_f32 v[82:83], v[82:83], v[178:179] op_sel_hi:[1,0] neg_lo:[0,1] neg_hi:[0,1]
	v_pk_mul_f32 v[82:83], v[178:179], v[82:83] op_sel:[1,0]
	v_pk_fma_f32 v[82:83], v[82:83], v[122:123], v[118:119]
	v_pk_add_f32 v[158:159], v[158:159], v[82:83]
	v_pk_add_f32 v[84:85], v[84:85], v[178:179] op_sel_hi:[1,0] neg_lo:[0,1] neg_hi:[0,1]
	v_pk_mul_f32 v[84:85], v[178:179], v[84:85] op_sel:[1,0]
	v_pk_fma_f32 v[84:85], v[84:85], v[112:113], v[124:125]
	v_pk_add_f32 v[152:153], v[152:153], v[84:85]
	v_pk_add_f32 v[86:87], v[86:87], v[178:179] op_sel_hi:[1,0] neg_lo:[0,1] neg_hi:[0,1]
	v_pk_mul_f32 v[86:87], v[178:179], v[86:87] op_sel:[1,0]
	v_pk_fma_f32 v[86:87], v[86:87], v[114:115], v[126:127]
	v_pk_add_f32 v[154:155], v[154:155], v[86:87]
	v_pk_mul_f32 v[106:107], v[156:157], v[156:157]
	v_pk_add_f32 v[104:105], v[156:157], v[158:159]
	v_pk_fma_f32 v[106:107], v[158:159], v[158:159], v[106:107]
	v_pk_add_f32 v[104:105], v[104:105], v[152:153]
	v_pk_fma_f32 v[106:107], v[152:153], v[152:153], v[106:107]
	v_pk_add_f32 v[104:105], v[104:105], v[154:155]
	v_pk_fma_f32 v[106:107], v[154:155], v[154:155], v[106:107]
	s_waitcnt vmcnt(5)
; #define EPI_FOR_ROWS for (int ai = 0; ai < 2; ++ai) _Pragma("unroll") for (int m = 0; m < 4; ++m)
; __device__ __forceinline__ void unpack8(const u32x4 w, f32x4& a, f32x4& b) { a = (f32x4){bf_lo(w.x), bf_hi(w.x), bf_lo(w.y), bf_hi(w.y)}; b = (f32x4){bf_lo(w.z), bf_hi(w.z), bf_lo(w.w), bf_hi(w.w)}; }
;     __device__ __forceinline__ void piece(size_t row, int col, f32x4 v0, f32x4 v1, const f32x4 a0, const f32x4 a1, const f32x4 b0, const f32x4 b1, const f32x4 c0, const f32x4 c1,
;                                           float mean, float rstd, float& s, float& ss) const {
;     ...
;         if constexpr (RECOMP) { f32x4 r0, r1; unpack8(*(const u32x4*)(Tin + row * DM + col), r0, r1);
;             r0 = (r0 - mean) * rstd * a0 + b0; r1 = (r1 - mean) * rstd * a1 + b1; v0 = r0 * ALPHA + v0; v1 = r1 * ALPHA + v1;
;             if constexpr (MODE == 5) { v0 = v0 + c0; v1 = v1 + c1; } }
;         if constexpr (MODE == 4) { v0 = (v0 - a0 * mean) * rstd + b0; v1 = (v1 - a1 * mean) * rstd + b1;
; #pragma unroll
;             for (int e = 0; e < 4; ++e) { const float x = fmaxf(v0[e], 0.f), y = fmaxf(v1[e], 0.f); v0[e] = x * x; v1[e] = y * y; } }
;         if constexpr (PROD) {
; #pragma unroll
;             for (int e = 0; e < 4; ++e) { s += v0[e] + v1[e]; ss += v0[e] * v0[e] + v1[e] * v1[e]; } }
;     __device__ __forceinline__ void operator()(const f32x4 (&acc)[2][2][4][2], const Unit& u, int wr, int wc, int fr_, int fq_, LAS unsigned char* ldsx) const {
;     ...
;         EPI_FOR_ROWS {
;             const int rl = ai * HALF + wr * 64 + m * 16 + fr; const size_t row = (size_t)u.row0 + rl;
;             float mean = 0.f, rstd = 0.f; if constexpr (CONS) { const f32x2 st = X[rl]; mean = st.x; rstd = st.y; }
;             float s = 0.f, ss = 0.f;
; #pragma unroll
;             for (int bj = 0; bj < 2; ++bj) piece(row, colb + bj * HALF, acc[ai][bj][m][0], acc[ai][bj][m][1], av[bj][0], av[bj][1], bv[bj][0], bv[bj][1], cv[bj][0], cv[bj][1], mean, rstd, s, ss);
;             if constexpr (PROD) { s += __shfl_xor(s, 16); ss += __shfl_xor(ss, 16); s += __shfl_xor(s, 32); ss += __shfl_xor(ss, 32);
;                 if (fq == 0) st_out[row * 16 + (u.col0 >> 8) * 4 + wc] = (f32x2){s, ss}; }
;         }
	v_lshlrev_b32_e32 v80, 16, v226
	v_and_b32_e32 v81, 0xffff0000, v226
	v_lshlrev_b32_e32 v82, 16, v227
	v_and_b32_e32 v83, 0xffff0000, v227
	v_lshlrev_b32_e32 v84, 16, v228
	v_and_b32_e32 v85, 0xffff0000, v228
	v_lshlrev_b32_e32 v86, 16, v229
	v_and_b32_e32 v87, 0xffff0000, v229
	v_add_u32_e32 v250, 0x80, v198
	v_ashrrev_i32_e32 v251, 31, v250
	v_lshl_add_u64 v[250:251], v[250:251], 0, s[20:21]
	v_lshlrev_b64 v[250:251], 11, v[250:251]
	v_lshl_add_u64 v[250:251], s[88:89], 0, v[250:251]
	v_lshl_add_u64 v[250:251], v[250:251], 0, v[200:201]
	global_load_dwordx4 v[226:229], v[250:251], off offset:256
	v_pk_add_f32 v[80:81], v[80:81], v[178:179] op_sel_hi:[1,0] neg_lo:[0,1] neg_hi:[0,1]
	v_pk_mul_f32 v[80:81], v[178:179], v[80:81] op_sel:[1,0]
	v_pk_fma_f32 v[80:81], v[80:81], v[96:97], v[100:101]
	v_pk_add_f32 v[148:149], v[148:149], v[80:81]
	v_pk_add_f32 v[82:83], v[82:83], v[178:179] op_sel_hi:[1,0] neg_lo:[0,1] neg_hi:[0,1]
	v_pk_mul_f32 v[82:83], v[178:179], v[82:83] op_sel:[1,0]
	v_pk_fma_f32 v[82:83], v[82:83], v[98:99], v[102:103]
	v_pk_add_f32 v[150:151], v[150:151], v[82:83]
	v_pk_add_f32 v[84:85], v[84:85], v[178:179] op_sel_hi:[1,0] neg_lo:[0,1] neg_hi:[0,1]
	v_pk_mul_f32 v[84:85], v[178:179], v[84:85] op_sel:[1,0]
	v_pk_fma_f32 v[84:85], v[84:85], v[88:89], v[92:93]
	v_pk_add_f32 v[144:145], v[144:145], v[84:85]
	v_pk_add_f32 v[86:87], v[86:87], v[178:179] op_sel_hi:[1,0] neg_lo:[0,1] neg_hi:[0,1]
	v_pk_mul_f32 v[86:87], v[178:179], v[86:87] op_sel:[1,0]
	v_pk_fma_f32 v[86:87], v[86:87], v[90:91], v[94:95]
	v_pk_add_f32 v[146:147], v[146:147], v[86:87]
	v_pk_add_f32 v[104:105], v[104:105], v[148:149]
	v_pk_fma_f32 v[106:107], v[148:149], v[148:149], v[106:107]
	v_pk_add_f32 v[104:105], v[104:105], v[150:151]
	v_pk_fma_f32 v[106:107], v[150:151], v[150:151], v[106:107]
	v_pk_add_f32 v[104:105], v[104:105], v[144:145]
	v_pk_fma_f32 v[106:107], v[144:145], v[144:145], v[106:107]
	v_pk_add_f32 v[104:105], v[104:105], v[146:147]
	v_pk_fma_f32 v[106:107], v[146:147], v[146:147], v[106:107]
	v_add_f32_e32 v108, v104, v105
	v_add_f32_e32 v109, v106, v107
	s_nop 0
	ds_bpermute_b32 v104, v110, v108
	ds_bpermute_b32 v105, v110, v109
	s_waitcnt lgkmcnt(0)
	v_pk_add_f32 v[108:109], v[108:109], v[104:105]
	s_nop 0
	ds_bpermute_b32 v104, v111, v108
	ds_bpermute_b32 v105, v111, v109
	s_waitcnt lgkmcnt(0)
	v_pk_add_f32 v[108:109], v[108:109], v[104:105]
	ds_write_b64 v252, v[108:109] offset:512
	s_waitcnt vmcnt(5)
	v_lshlrev_b32_e32 v80, 16, v230
	v_and_b32_e32 v81, 0xffff0000, v230
	v_lshlrev_b32_e32 v82, 16, v231
	v_and_b32_e32 v83, 0xffff0000, v231
	v_lshlrev_b32_e32 v84, 16, v232
	v_and_b32_e32 v85, 0xffff0000, v232
	v_lshlrev_b32_e32 v86, 16, v233
	v_and_b32_e32 v87, 0xffff0000, v233
	v_add_u32_e32 v250, 0x90, v198
	v_ashrrev_i32_e32 v251, 31, v250
	v_lshl_add_u64 v[250:251], v[250:251], 0, s[20:21]
	v_lshlrev_b64 v[250:251], 11, v[250:251]
	v_lshl_add_u64 v[250:251], s[88:89], 0, v[250:251]
	v_lshl_add_u64 v[250:251], v[250:251], 0, v[200:201]
	global_load_dwordx4 v[230:233], v[250:251], off
	v_pk_add_f32 v[80:81], v[80:81], v[238:239] op_sel_hi:[1,0] neg_lo:[0,1] neg_hi:[0,1]
	v_pk_mul_f32 v[80:81], v[238:239], v[80:81] op_sel:[1,0]
	v_pk_fma_f32 v[80:81], v[80:81], v[120:121], v[116:117]
	v_pk_add_f32 v[140:141], v[140:141], v[80:81]
	v_pk_add_f32 v[82:83], v[82:83], v[238:239] op_sel_hi:[1,0] neg_lo:[0,1] neg_hi:[0,1]
	v_pk_mul_f32 v[82:83], v[238:239], v[82:83] op_sel:[1,0]
	v_pk_fma_f32 v[82:83], v[82:83], v[122:123], v[118:119]
	v_pk_add_f32 v[142:143], v[142:143], v[82:83]
	v_pk_add_f32 v[84:85], v[84:85], v[238:239] op_sel_hi:[1,0] neg_lo:[0,1] neg_hi:[0,1]
	v_pk_mul_f32 v[84:85], v[238:239], v[84:85] op_sel:[1,0]
	v_pk_fma_f32 v[84:85], v[84:85], v[112:113], v[124:125]
	v_pk_add_f32 v[136:137], v[136:137], v[84:85]
	v_pk_add_f32 v[86:87], v[86:87], v[238:239] op_sel_hi:[1,0] neg_lo:[0,1] neg_hi:[0,1]
	v_pk_mul_f32 v[86:87], v[238:239], v[86:87] op_sel:[1,0]
	v_pk_fma_f32 v[86:87], v[86:87], v[114:115], v[126:127]
	v_pk_add_f32 v[138:139], v[138:139], v[86:87]
	v_pk_mul_f32 v[106:107], v[140:141], v[140:141]
	v_pk_add_f32 v[104:105], v[140:141], v[142:143]
	v_pk_fma_f32 v[106:107], v[142:143], v[142:143], v[106:107]
	v_pk_add_f32 v[104:105], v[104:105], v[136:137]
	v_pk_fma_f32 v[106:107], v[136:137], v[136:137], v[106:107]
	v_pk_add_f32 v[104:105], v[104:105], v[138:139]
	v_pk_fma_f32 v[106:107], v[138:139], v[138:139], v[106:107]
	s_waitcnt vmcnt(5)
	v_lshlrev_b32_e32 v80, 16, v234
	v_and_b32_e32 v81, 0xffff0000, v234
	v_lshlrev_b32_e32 v82, 16, v235
	v_and_b32_e32 v83, 0xffff0000, v235
	v_lshlrev_b32_e32 v84, 16, v236
	v_and_b32_e32 v85, 0xffff0000, v236
	v_lshlrev_b32_e32 v86, 16, v237
	v_and_b32_e32 v87, 0xffff0000, v237
	v_add_u32_e32 v250, 0x90, v198
	v_ashrrev_i32_e32 v251, 31, v250
	v_lshl_add_u64 v[250:251], v[250:251], 0, s[20:21]
	v_lshlrev_b64 v[250:251], 11, v[250:251]
	v_lshl_add_u64 v[250:251], s[88:89], 0, v[250:251]
	v_lshl_add_u64 v[250:251], v[250:251], 0, v[200:201]
	global_load_dwordx4 v[234:237], v[250:251], off offset:256
	v_pk_add_f32 v[80:81], v[80:81], v[238:239] op_sel_hi:[1,0] neg_lo:[0,1] neg_hi:[0,1]
	v_pk_mul_f32 v[80:81], v[238:239], v[80:81] op_sel:[1,0]
	v_pk_fma_f32 v[80:81], v[80:81], v[96:97], v[100:101]
	v_pk_add_f32 v[132:133], v[132:133], v[80:81]
	v_pk_add_f32 v[82:83], v[82:83], v[238:239] op_sel_hi:[1,0] neg_lo:[0,1] neg_hi:[0,1]
	v_pk_mul_f32 v[82:83], v[238:239], v[82:83] op_sel:[1,0]
	v_pk_fma_f32 v[82:83], v[82:83], v[98:99], v[102:103]
	v_pk_add_f32 v[134:135], v[134:135], v[82:83]
	v_pk_add_f32 v[84:85], v[84:85], v[238:239] op_sel_hi:[1,0] neg_lo:[0,1] neg_hi:[0,1]
	v_pk_mul_f32 v[84:85], v[238:239], v[84:85] op_sel:[1,0]
	v_pk_fma_f32 v[84:85], v[84:85], v[88:89], v[92:93]
	v_pk_add_f32 v[128:129], v[128:129], v[84:85]
	v_pk_add_f32 v[86:87], v[86:87], v[238:239] op_sel_hi:[1,0] neg_lo:[0,1] neg_hi:[0,1]
	v_pk_mul_f32 v[86:87], v[238:239], v[86:87] op_sel:[1,0]
	v_pk_fma_f32 v[86:87], v[86:87], v[90:91], v[94:95]
	v_pk_add_f32 v[130:131], v[130:131], v[86:87]
	v_pk_add_f32 v[104:105], v[104:105], v[132:133]
	v_pk_fma_f32 v[106:107], v[132:133], v[132:133], v[106:107]
	v_pk_add_f32 v[104:105], v[104:105], v[134:135]
	v_pk_fma_f32 v[106:107], v[134:135], v[134:135], v[106:107]
	v_pk_add_f32 v[104:105], v[104:105], v[128:129]
	v_pk_fma_f32 v[106:107], v[128:129], v[128:129], v[106:107]
	v_pk_add_f32 v[104:105], v[104:105], v[130:131]
	v_pk_fma_f32 v[106:107], v[130:131], v[130:131], v[106:107]
	v_add_f32_e32 v108, v104, v105
	v_add_f32_e32 v109, v106, v107
	s_nop 0
	ds_bpermute_b32 v104, v110, v108
	ds_bpermute_b32 v105, v110, v109
	s_waitcnt lgkmcnt(0)
; #define EPI_FOR_ROWS for (int ai = 0; ai < 2; ++ai) _Pragma("unroll") for (int m = 0; m < 4; ++m)
; __device__ __forceinline__ void unpack8(const u32x4 w, f32x4& a, f32x4& b) { a = (f32x4){bf_lo(w.x), bf_hi(w.x), bf_lo(w.y), bf_hi(w.y)}; b = (f32x4){bf_lo(w.z), bf_hi(w.z), bf_lo(w.w), bf_hi(w.w)}; }
;     __device__ __forceinline__ void piece(size_t row, int col, f32x4 v0, f32x4 v1, const f32x4 a0, const f32x4 a1, const f32x4 b0, const f32x4 b1, const f32x4 c0, const f32x4 c1,
;                                           float mean, float rstd, float& s, float& ss) const {
;     ...
;         if constexpr (RECOMP) { f32x4 r0, r1; unpack8(*(const u32x4*)(Tin + row * DM + col), r0, r1);
;             r0 = (r0 - mean) * rstd * a0 + b0; r1 = (r1 - mean) * rstd * a1 + b1; v0 = r0 * ALPHA + v0; v1 = r1 * ALPHA + v1;
;             if constexpr (MODE == 5) { v0 = v0 + c0; v1 = v1 + c1; } }
;         if constexpr (MODE == 4) { v0 = (v0 - a0 * mean) * rstd + b0; v1 = (v1 - a1 * mean) * rstd + b1;
; #pragma unroll
;             for (int e = 0; e < 4; ++e) { const float x = fmaxf(v0[e], 0.f), y = fmaxf(v1[e], 0.f); v0[e] = x * x; v1[e] = y * y; } }
;         if constexpr (PROD) {
; #pragma unroll
;             for (int e = 0; e < 4; ++e) { s += v0[e] + v1[e]; ss += v0[e] * v0[e] + v1[e] * v1[e]; } }
;     __device__ __forceinline__ void operator()(const f32x4 (&acc)[2][2][4][2], const Unit& u, int wr, int wc, int fr_, int fq_, LAS unsigned char* ldsx) const {
;     ...
;         EPI_FOR_ROWS {
;             const int rl = ai * HALF + wr * 64 + m * 16 + fr; const size_t row = (size_t)u.row0 + rl;
;             float mean = 0.f, rstd = 0.f; if constexpr (CONS) { const f32x2 st = X[rl]; mean = st.x; rstd = st.y; }
;             float s = 0.f, ss = 0.f;
; #pragma unroll
;             for (int bj = 0; bj < 2; ++bj) piece(row, colb + bj * HALF, acc[ai][bj][m][0], acc[ai][bj][m][1], av[bj][0], av[bj][1], bv[bj][0], bv[bj][1], cv[bj][0], cv[bj][1], mean, rstd, s, ss);
;             if constexpr (PROD) { s += __shfl_xor(s, 16); ss += __shfl_xor(ss, 16); s += __shfl_xor(s, 32); ss += __shfl_xor(ss, 32);
;                 if (fq == 0) st_out[row * 16 + (u.col0 >> 8) * 4 + wc] = (f32x2){s, ss}; }
;         }
	v_pk_add_f32 v[108:109], v[108:109], v[104:105]
	s_nop 0
	ds_bpermute_b32 v104, v111, v108
	ds_bpermute_b32 v105, v111, v109
	s_waitcnt lgkmcnt(0)
	v_pk_add_f32 v[108:109], v[108:109], v[104:105]
	ds_write_b64 v252, v[108:109] offset:1024
	s_waitcnt vmcnt(5)
	v_lshlrev_b32_e32 v80, 16, v210
	v_and_b32_e32 v81, 0xffff0000, v210
	v_lshlrev_b32_e32 v82, 16, v211
	v_and_b32_e32 v83, 0xffff0000, v211
	v_lshlrev_b32_e32 v84, 16, v212
	v_and_b32_e32 v85, 0xffff0000, v212
	v_lshlrev_b32_e32 v86, 16, v213
	v_and_b32_e32 v87, 0xffff0000, v213
	v_add_u32_e32 v250, 0xa0, v198
	v_ashrrev_i32_e32 v251, 31, v250
	v_lshl_add_u64 v[250:251], v[250:251], 0, s[20:21]
	v_lshlrev_b64 v[250:251], 11, v[250:251]
	v_lshl_add_u64 v[250:251], s[88:89], 0, v[250:251]
	v_lshl_add_u64 v[250:251], v[250:251], 0, v[200:201]
	global_load_dwordx4 v[210:213], v[250:251], off
	v_pk_add_f32 v[80:81], v[80:81], v[240:241] op_sel_hi:[1,0] neg_lo:[0,1] neg_hi:[0,1]
	v_pk_mul_f32 v[80:81], v[240:241], v[80:81] op_sel:[1,0]
	v_pk_fma_f32 v[80:81], v[80:81], v[120:121], v[116:117]
	v_pk_add_f32 v[76:77], v[76:77], v[80:81]
	v_pk_add_f32 v[82:83], v[82:83], v[240:241] op_sel_hi:[1,0] neg_lo:[0,1] neg_hi:[0,1]
	v_pk_mul_f32 v[82:83], v[240:241], v[82:83] op_sel:[1,0]
	v_pk_fma_f32 v[82:83], v[82:83], v[122:123], v[118:119]
	v_pk_add_f32 v[78:79], v[78:79], v[82:83]
	v_pk_add_f32 v[84:85], v[84:85], v[240:241] op_sel_hi:[1,0] neg_lo:[0,1] neg_hi:[0,1]
	v_pk_mul_f32 v[84:85], v[240:241], v[84:85] op_sel:[1,0]
	v_pk_fma_f32 v[84:85], v[84:85], v[112:113], v[124:125]
	v_pk_add_f32 v[72:73], v[72:73], v[84:85]
	v_pk_add_f32 v[86:87], v[86:87], v[240:241] op_sel_hi:[1,0] neg_lo:[0,1] neg_hi:[0,1]
	v_pk_mul_f32 v[86:87], v[240:241], v[86:87] op_sel:[1,0]
	v_pk_fma_f32 v[86:87], v[86:87], v[114:115], v[126:127]
	v_pk_add_f32 v[74:75], v[74:75], v[86:87]
	v_pk_mul_f32 v[106:107], v[76:77], v[76:77]
	v_pk_add_f32 v[104:105], v[76:77], v[78:79]
	v_pk_fma_f32 v[106:107], v[78:79], v[78:79], v[106:107]
	v_pk_add_f32 v[104:105], v[104:105], v[72:73]
	v_pk_fma_f32 v[106:107], v[72:73], v[72:73], v[106:107]
	v_pk_add_f32 v[104:105], v[104:105], v[74:75]
	v_pk_fma_f32 v[106:107], v[74:75], v[74:75], v[106:107]
	s_waitcnt vmcnt(5)
	v_lshlrev_b32_e32 v80, 16, v218
	v_and_b32_e32 v81, 0xffff0000, v218
	v_lshlrev_b32_e32 v82, 16, v219
	v_and_b32_e32 v83, 0xffff0000, v219
	v_lshlrev_b32_e32 v84, 16, v220
	v_and_b32_e32 v85, 0xffff0000, v220
	v_lshlrev_b32_e32 v86, 16, v221
	v_and_b32_e32 v87, 0xffff0000, v221
	v_add_u32_e32 v250, 0xa0, v198
	v_ashrrev_i32_e32 v251, 31, v250
	v_lshl_add_u64 v[250:251], v[250:251], 0, s[20:21]
	v_lshlrev_b64 v[250:251], 11, v[250:251]
	v_lshl_add_u64 v[250:251], s[88:89], 0, v[250:251]
	v_lshl_add_u64 v[250:251], v[250:251], 0, v[200:201]
	global_load_dwordx4 v[218:221], v[250:251], off offset:256
	v_pk_add_f32 v[80:81], v[80:81], v[240:241] op_sel_hi:[1,0] neg_lo:[0,1] neg_hi:[0,1]
	v_pk_mul_f32 v[80:81], v[240:241], v[80:81] op_sel:[1,0]
	v_pk_fma_f32 v[80:81], v[80:81], v[96:97], v[100:101]
	v_pk_add_f32 v[68:69], v[68:69], v[80:81]
	v_pk_add_f32 v[82:83], v[82:83], v[240:241] op_sel_hi:[1,0] neg_lo:[0,1] neg_hi:[0,1]
	v_pk_mul_f32 v[82:83], v[240:241], v[82:83] op_sel:[1,0]
	v_pk_fma_f32 v[82:83], v[82:83], v[98:99], v[102:103]
	v_pk_add_f32 v[70:71], v[70:71], v[82:83]
	v_pk_add_f32 v[84:85], v[84:85], v[240:241] op_sel_hi:[1,0] neg_lo:[0,1] neg_hi:[0,1]
	v_pk_mul_f32 v[84:85], v[240:241], v[84:85] op_sel:[1,0]
	v_pk_fma_f32 v[84:85], v[84:85], v[88:89], v[92:93]
	v_pk_add_f32 v[64:65], v[64:65], v[84:85]
	v_pk_add_f32 v[86:87], v[86:87], v[240:241] op_sel_hi:[1,0] neg_lo:[0,1] neg_hi:[0,1]
	v_pk_mul_f32 v[86:87], v[240:241], v[86:87] op_sel:[1,0]
	v_pk_fma_f32 v[86:87], v[86:87], v[90:91], v[94:95]
	v_pk_add_f32 v[66:67], v[66:67], v[86:87]
	v_pk_add_f32 v[104:105], v[104:105], v[68:69]
	v_pk_fma_f32 v[106:107], v[68:69], v[68:69], v[106:107]
	v_pk_add_f32 v[104:105], v[104:105], v[70:71]
	v_pk_fma_f32 v[106:107], v[70:71], v[70:71], v[106:107]
	v_pk_add_f32 v[104:105], v[104:105], v[64:65]
	v_pk_fma_f32 v[106:107], v[64:65], v[64:65], v[106:107]
	v_pk_add_f32 v[104:105], v[104:105], v[66:67]
	v_pk_fma_f32 v[106:107], v[66:67], v[66:67], v[106:107]
	v_add_f32_e32 v108, v104, v105
	v_add_f32_e32 v109, v106, v107
	s_nop 0
	ds_bpermute_b32 v104, v110, v108
	ds_bpermute_b32 v105, v110, v109
	s_waitcnt lgkmcnt(0)
	v_pk_add_f32 v[108:109], v[108:109], v[104:105]
	s_nop 0
	ds_bpermute_b32 v104, v111, v108
	ds_bpermute_b32 v105, v111, v109
	s_waitcnt lgkmcnt(0)
	v_pk_add_f32 v[108:109], v[108:109], v[104:105]
	ds_write_b64 v252, v[108:109] offset:1536
	s_waitcnt vmcnt(5)
	v_lshlrev_b32_e32 v80, 16, v222
	v_and_b32_e32 v81, 0xffff0000, v222
	v_lshlrev_b32_e32 v82, 16, v223
	v_and_b32_e32 v83, 0xffff0000, v223
	v_lshlrev_b32_e32 v84, 16, v224
	v_and_b32_e32 v85, 0xffff0000, v224
	v_lshlrev_b32_e32 v86, 16, v225
	v_and_b32_e32 v87, 0xffff0000, v225
	v_add_u32_e32 v250, 0xb0, v198
	v_ashrrev_i32_e32 v251, 31, v250
	v_lshl_add_u64 v[250:251], v[250:251], 0, s[20:21]
	v_lshlrev_b64 v[250:251], 11, v[250:251]
	v_lshl_add_u64 v[250:251], s[88:89], 0, v[250:251]
	v_lshl_add_u64 v[250:251], v[250:251], 0, v[200:201]
	global_load_dwordx4 v[222:225], v[250:251], off
	v_pk_add_f32 v[80:81], v[80:81], v[242:243] op_sel_hi:[1,0] neg_lo:[0,1] neg_hi:[0,1]
	v_pk_mul_f32 v[80:81], v[242:243], v[80:81] op_sel:[1,0]
	v_pk_fma_f32 v[80:81], v[80:81], v[120:121], v[116:117]
	v_pk_add_f32 v[60:61], v[60:61], v[80:81]
	v_pk_add_f32 v[82:83], v[82:83], v[242:243] op_sel_hi:[1,0] neg_lo:[0,1] neg_hi:[0,1]
	v_pk_mul_f32 v[82:83], v[242:243], v[82:83] op_sel:[1,0]
	v_pk_fma_f32 v[82:83], v[82:83], v[122:123], v[118:119]
	v_pk_add_f32 v[62:63], v[62:63], v[82:83]
	v_pk_add_f32 v[84:85], v[84:85], v[242:243] op_sel_hi:[1,0] neg_lo:[0,1] neg_hi:[0,1]
	v_pk_mul_f32 v[84:85], v[242:243], v[84:85] op_sel:[1,0]
	v_pk_fma_f32 v[84:85], v[84:85], v[112:113], v[124:125]
	v_pk_add_f32 v[56:57], v[56:57], v[84:85]
	v_pk_add_f32 v[86:87], v[86:87], v[242:243] op_sel_hi:[1,0] neg_lo:[0,1] neg_hi:[0,1]
	v_pk_mul_f32 v[86:87], v[242:243], v[86:87] op_sel:[1,0]
	v_pk_fma_f32 v[86:87], v[86:87], v[114:115], v[126:127]
	v_pk_add_f32 v[58:59], v[58:59], v[86:87]
	v_pk_mul_f32 v[106:107], v[60:61], v[60:61]
	v_pk_add_f32 v[104:105], v[60:61], v[62:63]
	v_pk_fma_f32 v[106:107], v[62:63], v[62:63], v[106:107]
	v_pk_add_f32 v[104:105], v[104:105], v[56:57]
	v_pk_fma_f32 v[106:107], v[56:57], v[56:57], v[106:107]
	v_pk_add_f32 v[104:105], v[104:105], v[58:59]
	v_pk_fma_f32 v[106:107], v[58:59], v[58:59], v[106:107]
	s_waitcnt vmcnt(5)
; #define EPI_FOR_ROWS for (int ai = 0; ai < 2; ++ai) _Pragma("unroll") for (int m = 0; m < 4; ++m)
; __device__ __forceinline__ void unpack8(const u32x4 w, f32x4& a, f32x4& b) { a = (f32x4){bf_lo(w.x), bf_hi(w.x), bf_lo(w.y), bf_hi(w.y)}; b = (f32x4){bf_lo(w.z), bf_hi(w.z), bf_lo(w.w), bf_hi(w.w)}; }
;     __device__ __forceinline__ void piece(size_t row, int col, f32x4 v0, f32x4 v1, const f32x4 a0, const f32x4 a1, const f32x4 b0, const f32x4 b1, const f32x4 c0, const f32x4 c1,
;                                           float mean, float rstd, float& s, float& ss) const {
;     ...
;         if constexpr (RECOMP) { f32x4 r0, r1; unpack8(*(const u32x4*)(Tin + row * DM + col), r0, r1);
;             r0 = (r0 - mean) * rstd * a0 + b0; r1 = (r1 - mean) * rstd * a1 + b1; v0 = r0 * ALPHA + v0; v1 = r1 * ALPHA + v1;
;             if constexpr (MODE == 5) { v0 = v0 + c0; v1 = v1 + c1; } }
;         if constexpr (MODE == 4) { v0 = (v0 - a0 * mean) * rstd + b0; v1 = (v1 - a1 * mean) * rstd + b1;
; #pragma unroll
;             for (int e = 0; e < 4; ++e) { const float x = fmaxf(v0[e], 0.f), y = fmaxf(v1[e], 0.f); v0[e] = x * x; v1[e] = y * y; } }
;         if constexpr (PROD) {
; #pragma unroll
;             for (int e = 0; e < 4; ++e) { s += v0[e] + v1[e]; ss += v0[e] * v0[e] + v1[e] * v1[e]; } }
;     __device__ __forceinline__ void operator()(const f32x4 (&acc)[2][2][4][2], const Unit& u, int wr, int wc, int fr_, int fq_, LAS unsigned char* ldsx) const {
;     ...
;         EPI_FOR_ROWS {
;             const int rl = ai * HALF + wr * 64 + m * 16 + fr; const size_t row = (size_t)u.row0 + rl;
;             float mean = 0.f, rstd = 0.f; if constexpr (CONS) { const f32x2 st = X[rl]; mean = st.x; rstd = st.y; }
;             float s = 0.f, ss = 0.f;
; #pragma unroll
;             for (int bj = 0; bj < 2; ++bj) piece(row, colb + bj * HALF, acc[ai][bj][m][0], acc[ai][bj][m][1], av[bj][0], av[bj][1], bv[bj][0], bv[bj][1], cv[bj][0], cv[bj][1], mean, rstd, s, ss);
;             if constexpr (PROD) { s += __shfl_xor(s, 16); ss += __shfl_xor(ss, 16); s += __shfl_xor(s, 32); ss += __shfl_xor(ss, 32);
;                 if (fq == 0) st_out[row * 16 + (u.col0 >> 8) * 4 + wc] = (f32x2){s, ss}; }
;         }
	v_lshlrev_b32_e32 v80, 16, v226
	v_and_b32_e32 v81, 0xffff0000, v226
	v_lshlrev_b32_e32 v82, 16, v227
	v_and_b32_e32 v83, 0xffff0000, v227
	v_lshlrev_b32_e32 v84, 16, v228
	v_and_b32_e32 v85, 0xffff0000, v228
	v_lshlrev_b32_e32 v86, 16, v229
	v_and_b32_e32 v87, 0xffff0000, v229
	v_add_u32_e32 v250, 0xb0, v198
	v_ashrrev_i32_e32 v251, 31, v250
	v_lshl_add_u64 v[250:251], v[250:251], 0, s[20:21]
	v_lshlrev_b64 v[250:251], 11, v[250:251]
	v_lshl_add_u64 v[250:251], s[88:89], 0, v[250:251]
	v_lshl_add_u64 v[250:251], v[250:251], 0, v[200:201]
	global_load_dwordx4 v[226:229], v[250:251], off offset:256
	v_pk_add_f32 v[80:81], v[80:81], v[242:243] op_sel_hi:[1,0] neg_lo:[0,1] neg_hi:[0,1]
	v_pk_mul_f32 v[80:81], v[242:243], v[80:81] op_sel:[1,0]
	v_pk_fma_f32 v[80:81], v[80:81], v[96:97], v[100:101]
	v_pk_add_f32 v[52:53], v[52:53], v[80:81]
	v_pk_add_f32 v[82:83], v[82:83], v[242:243] op_sel_hi:[1,0] neg_lo:[0,1] neg_hi:[0,1]
	v_pk_mul_f32 v[82:83], v[242:243], v[82:83] op_sel:[1,0]
	v_pk_fma_f32 v[82:83], v[82:83], v[98:99], v[102:103]
	v_pk_add_f32 v[54:55], v[54:55], v[82:83]
	v_pk_add_f32 v[84:85], v[84:85], v[242:243] op_sel_hi:[1,0] neg_lo:[0,1] neg_hi:[0,1]
	v_pk_mul_f32 v[84:85], v[242:243], v[84:85] op_sel:[1,0]
	v_pk_fma_f32 v[84:85], v[84:85], v[88:89], v[92:93]
	v_pk_add_f32 v[48:49], v[48:49], v[84:85]
	v_pk_add_f32 v[86:87], v[86:87], v[242:243] op_sel_hi:[1,0] neg_lo:[0,1] neg_hi:[0,1]
	v_pk_mul_f32 v[86:87], v[242:243], v[86:87] op_sel:[1,0]
	v_pk_fma_f32 v[86:87], v[86:87], v[90:91], v[94:95]
	v_pk_add_f32 v[50:51], v[50:51], v[86:87]
	v_pk_add_f32 v[104:105], v[104:105], v[52:53]
	v_pk_fma_f32 v[106:107], v[52:53], v[52:53], v[106:107]
	v_pk_add_f32 v[104:105], v[104:105], v[54:55]
	v_pk_fma_f32 v[106:107], v[54:55], v[54:55], v[106:107]
	v_pk_add_f32 v[104:105], v[104:105], v[48:49]
	v_pk_fma_f32 v[106:107], v[48:49], v[48:49], v[106:107]
	v_pk_add_f32 v[104:105], v[104:105], v[50:51]
	v_pk_fma_f32 v[106:107], v[50:51], v[50:51], v[106:107]
	v_add_f32_e32 v108, v104, v105
	v_add_f32_e32 v109, v106, v107
	s_nop 0
	ds_bpermute_b32 v104, v110, v108
	ds_bpermute_b32 v105, v110, v109
	s_waitcnt lgkmcnt(0)
	v_pk_add_f32 v[108:109], v[108:109], v[104:105]
	s_nop 0
	ds_bpermute_b32 v104, v111, v108
	ds_bpermute_b32 v105, v111, v109
	s_waitcnt lgkmcnt(0)
	v_pk_add_f32 v[108:109], v[108:109], v[104:105]
	ds_write_b64 v252, v[108:109] offset:4096
	s_waitcnt vmcnt(5)
	v_lshlrev_b32_e32 v80, 16, v230
	v_and_b32_e32 v81, 0xffff0000, v230
	v_lshlrev_b32_e32 v82, 16, v231
	v_and_b32_e32 v83, 0xffff0000, v231
	v_lshlrev_b32_e32 v84, 16, v232
	v_and_b32_e32 v85, 0xffff0000, v232
	v_lshlrev_b32_e32 v86, 16, v233
	v_and_b32_e32 v87, 0xffff0000, v233
	v_pk_add_f32 v[80:81], v[80:81], v[244:245] op_sel_hi:[1,0] neg_lo:[0,1] neg_hi:[0,1]
	v_pk_mul_f32 v[80:81], v[244:245], v[80:81] op_sel:[1,0]
	v_pk_fma_f32 v[80:81], v[80:81], v[120:121], v[116:117]
	v_pk_add_f32 v[44:45], v[44:45], v[80:81]
	v_pk_add_f32 v[82:83], v[82:83], v[244:245] op_sel_hi:[1,0] neg_lo:[0,1] neg_hi:[0,1]
	v_pk_mul_f32 v[82:83], v[244:245], v[82:83] op_sel:[1,0]
	v_pk_fma_f32 v[82:83], v[82:83], v[122:123], v[118:119]
	v_pk_add_f32 v[46:47], v[46:47], v[82:83]
	v_pk_add_f32 v[84:85], v[84:85], v[244:245] op_sel_hi:[1,0] neg_lo:[0,1] neg_hi:[0,1]
	v_pk_mul_f32 v[84:85], v[244:245], v[84:85] op_sel:[1,0]
	v_pk_fma_f32 v[84:85], v[84:85], v[112:113], v[124:125]
	v_pk_add_f32 v[40:41], v[40:41], v[84:85]
	v_pk_add_f32 v[86:87], v[86:87], v[244:245] op_sel_hi:[1,0] neg_lo:[0,1] neg_hi:[0,1]
	v_pk_mul_f32 v[86:87], v[244:245], v[86:87] op_sel:[1,0]
	v_pk_fma_f32 v[86:87], v[86:87], v[114:115], v[126:127]
	v_pk_add_f32 v[42:43], v[42:43], v[86:87]
	v_pk_mul_f32 v[106:107], v[44:45], v[44:45]
	v_pk_add_f32 v[104:105], v[44:45], v[46:47]
	v_pk_fma_f32 v[106:107], v[46:47], v[46:47], v[106:107]
	v_pk_add_f32 v[104:105], v[104:105], v[40:41]
	v_pk_fma_f32 v[106:107], v[40:41], v[40:41], v[106:107]
	v_pk_add_f32 v[104:105], v[104:105], v[42:43]
	v_pk_fma_f32 v[106:107], v[42:43], v[42:43], v[106:107]
	s_waitcnt vmcnt(4)
	v_lshlrev_b32_e32 v80, 16, v234
	v_and_b32_e32 v81, 0xffff0000, v234
	v_lshlrev_b32_e32 v82, 16, v235
	v_and_b32_e32 v83, 0xffff0000, v235
	v_lshlrev_b32_e32 v84, 16, v236
	v_and_b32_e32 v85, 0xffff0000, v236
	v_lshlrev_b32_e32 v86, 16, v237
	v_and_b32_e32 v87, 0xffff0000, v237
	v_pk_add_f32 v[80:81], v[80:81], v[244:245] op_sel_hi:[1,0] neg_lo:[0,1] neg_hi:[0,1]
	v_pk_mul_f32 v[80:81], v[244:245], v[80:81] op_sel:[1,0]
	v_pk_fma_f32 v[80:81], v[80:81], v[96:97], v[100:101]
	v_pk_add_f32 v[36:37], v[36:37], v[80:81]
	v_pk_add_f32 v[82:83], v[82:83], v[244:245] op_sel_hi:[1,0] neg_lo:[0,1] neg_hi:[0,1]
	v_pk_mul_f32 v[82:83], v[244:245], v[82:83] op_sel:[1,0]
	v_pk_fma_f32 v[82:83], v[82:83], v[98:99], v[102:103]
	v_pk_add_f32 v[38:39], v[38:39], v[82:83]
	v_pk_add_f32 v[84:85], v[84:85], v[244:245] op_sel_hi:[1,0] neg_lo:[0,1] neg_hi:[0,1]
	v_pk_mul_f32 v[84:85], v[244:245], v[84:85] op_sel:[1,0]
	v_pk_fma_f32 v[84:85], v[84:85], v[88:89], v[92:93]
	v_pk_add_f32 v[32:33], v[32:33], v[84:85]
	v_pk_add_f32 v[86:87], v[86:87], v[244:245] op_sel_hi:[1,0] neg_lo:[0,1] neg_hi:[0,1]
	v_pk_mul_f32 v[86:87], v[244:245], v[86:87] op_sel:[1,0]
	v_pk_fma_f32 v[86:87], v[86:87], v[90:91], v[94:95]
	v_pk_add_f32 v[34:35], v[34:35], v[86:87]
	v_pk_add_f32 v[104:105], v[104:105], v[36:37]
	v_pk_fma_f32 v[106:107], v[36:37], v[36:37], v[106:107]
	v_pk_add_f32 v[104:105], v[104:105], v[38:39]
	v_pk_fma_f32 v[106:107], v[38:39], v[38:39], v[106:107]
	v_pk_add_f32 v[104:105], v[104:105], v[32:33]
	v_pk_fma_f32 v[106:107], v[32:33], v[32:33], v[106:107]
	v_pk_add_f32 v[104:105], v[104:105], v[34:35]
	v_pk_fma_f32 v[106:107], v[34:35], v[34:35], v[106:107]
	v_add_f32_e32 v108, v104, v105
	v_add_f32_e32 v109, v106, v107
	s_nop 0
	ds_bpermute_b32 v104, v110, v108
	ds_bpermute_b32 v105, v110, v109
	s_waitcnt lgkmcnt(0)
; #define EPI_FOR_ROWS for (int ai = 0; ai < 2; ++ai) _Pragma("unroll") for (int m = 0; m < 4; ++m)
; __device__ __forceinline__ void unpack8(const u32x4 w, f32x4& a, f32x4& b) { a = (f32x4){bf_lo(w.x), bf_hi(w.x), bf_lo(w.y), bf_hi(w.y)}; b = (f32x4){bf_lo(w.z), bf_hi(w.z), bf_lo(w.w), bf_hi(w.w)}; }
;     __device__ __forceinline__ void piece(size_t row, int col, f32x4 v0, f32x4 v1, const f32x4 a0, const f32x4 a1, const f32x4 b0, const f32x4 b1, const f32x4 c0, const f32x4 c1,
;                                           float mean, float rstd, float& s, float& ss) const {
;     ...
;         if constexpr (RECOMP) { f32x4 r0, r1; unpack8(*(const u32x4*)(Tin + row * DM + col), r0, r1);
;             r0 = (r0 - mean) * rstd * a0 + b0; r1 = (r1 - mean) * rstd * a1 + b1; v0 = r0 * ALPHA + v0; v1 = r1 * ALPHA + v1;
;             if constexpr (MODE == 5) { v0 = v0 + c0; v1 = v1 + c1; } }
;         if constexpr (MODE == 4) { v0 = (v0 - a0 * mean) * rstd + b0; v1 = (v1 - a1 * mean) * rstd + b1;
; #pragma unroll
;             for (int e = 0; e < 4; ++e) { const float x = fmaxf(v0[e], 0.f), y = fmaxf(v1[e], 0.f); v0[e] = x * x; v1[e] = y * y; } }
;         if constexpr (PROD) {
; #pragma unroll
;             for (int e = 0; e < 4; ++e) { s += v0[e] + v1[e]; ss += v0[e] * v0[e] + v1[e] * v1[e]; } }
;     __device__ __forceinline__ void operator()(const f32x4 (&acc)[2][2][4][2], const Unit& u, int wr, int wc, int fr_, int fq_, LAS unsigned char* ldsx) const {
;     ...
;         EPI_FOR_ROWS {
;             const int rl = ai * HALF + wr * 64 + m * 16 + fr; const size_t row = (size_t)u.row0 + rl;
;             float mean = 0.f, rstd = 0.f; if constexpr (CONS) { const f32x2 st = X[rl]; mean = st.x; rstd = st.y; }
;             float s = 0.f, ss = 0.f;
; #pragma unroll
;             for (int bj = 0; bj < 2; ++bj) piece(row, colb + bj * HALF, acc[ai][bj][m][0], acc[ai][bj][m][1], av[bj][0], av[bj][1], bv[bj][0], bv[bj][1], cv[bj][0], cv[bj][1], mean, rstd, s, ss);
;             if constexpr (PROD) { s += __shfl_xor(s, 16); ss += __shfl_xor(ss, 16); s += __shfl_xor(s, 32); ss += __shfl_xor(ss, 32);
;                 if (fq == 0) st_out[row * 16 + (u.col0 >> 8) * 4 + wc] = (f32x2){s, ss}; }
;         }
	v_pk_add_f32 v[108:109], v[108:109], v[104:105]
	s_nop 0
	ds_bpermute_b32 v104, v111, v108
	ds_bpermute_b32 v105, v111, v109
	s_waitcnt lgkmcnt(0)
	v_pk_add_f32 v[108:109], v[108:109], v[104:105]
	ds_write_b64 v252, v[108:109] offset:4608
	s_waitcnt vmcnt(3)
	v_lshlrev_b32_e32 v80, 16, v210
	v_and_b32_e32 v81, 0xffff0000, v210
	v_lshlrev_b32_e32 v82, 16, v211
	v_and_b32_e32 v83, 0xffff0000, v211
	v_lshlrev_b32_e32 v84, 16, v212
	v_and_b32_e32 v85, 0xffff0000, v212
	v_lshlrev_b32_e32 v86, 16, v213
	v_and_b32_e32 v87, 0xffff0000, v213
	v_pk_add_f32 v[80:81], v[80:81], v[246:247] op_sel_hi:[1,0] neg_lo:[0,1] neg_hi:[0,1]
	v_pk_mul_f32 v[80:81], v[246:247], v[80:81] op_sel:[1,0]
	v_pk_fma_f32 v[80:81], v[80:81], v[120:121], v[116:117]
	v_pk_add_f32 v[28:29], v[28:29], v[80:81]
	v_pk_add_f32 v[82:83], v[82:83], v[246:247] op_sel_hi:[1,0] neg_lo:[0,1] neg_hi:[0,1]
	v_pk_mul_f32 v[82:83], v[246:247], v[82:83] op_sel:[1,0]
	v_pk_fma_f32 v[82:83], v[82:83], v[122:123], v[118:119]
	v_pk_add_f32 v[30:31], v[30:31], v[82:83]
	v_pk_add_f32 v[84:85], v[84:85], v[246:247] op_sel_hi:[1,0] neg_lo:[0,1] neg_hi:[0,1]
	v_pk_mul_f32 v[84:85], v[246:247], v[84:85] op_sel:[1,0]
	v_pk_fma_f32 v[84:85], v[84:85], v[112:113], v[124:125]
	v_pk_add_f32 v[24:25], v[24:25], v[84:85]
	v_pk_add_f32 v[86:87], v[86:87], v[246:247] op_sel_hi:[1,0] neg_lo:[0,1] neg_hi:[0,1]
	v_pk_mul_f32 v[86:87], v[246:247], v[86:87] op_sel:[1,0]
	v_pk_fma_f32 v[86:87], v[86:87], v[114:115], v[126:127]
	v_pk_add_f32 v[26:27], v[26:27], v[86:87]
	v_pk_mul_f32 v[106:107], v[28:29], v[28:29]
	v_pk_add_f32 v[104:105], v[28:29], v[30:31]
	v_pk_fma_f32 v[106:107], v[30:31], v[30:31], v[106:107]
	v_pk_add_f32 v[104:105], v[104:105], v[24:25]
	v_pk_fma_f32 v[106:107], v[24:25], v[24:25], v[106:107]
	v_pk_add_f32 v[104:105], v[104:105], v[26:27]
	v_pk_fma_f32 v[106:107], v[26:27], v[26:27], v[106:107]
	s_waitcnt vmcnt(2)
	v_lshlrev_b32_e32 v80, 16, v218
	v_and_b32_e32 v81, 0xffff0000, v218
	v_lshlrev_b32_e32 v82, 16, v219
	v_and_b32_e32 v83, 0xffff0000, v219
	v_lshlrev_b32_e32 v84, 16, v220
	v_and_b32_e32 v85, 0xffff0000, v220
	v_lshlrev_b32_e32 v86, 16, v221
	v_and_b32_e32 v87, 0xffff0000, v221
	v_pk_add_f32 v[80:81], v[80:81], v[246:247] op_sel_hi:[1,0] neg_lo:[0,1] neg_hi:[0,1]
	v_pk_mul_f32 v[80:81], v[246:247], v[80:81] op_sel:[1,0]
	v_pk_fma_f32 v[80:81], v[80:81], v[96:97], v[100:101]
	v_pk_add_f32 v[20:21], v[20:21], v[80:81]
	v_pk_add_f32 v[82:83], v[82:83], v[246:247] op_sel_hi:[1,0] neg_lo:[0,1] neg_hi:[0,1]
	v_pk_mul_f32 v[82:83], v[246:247], v[82:83] op_sel:[1,0]
	v_pk_fma_f32 v[82:83], v[82:83], v[98:99], v[102:103]
	v_pk_add_f32 v[22:23], v[22:23], v[82:83]
	v_pk_add_f32 v[84:85], v[84:85], v[246:247] op_sel_hi:[1,0] neg_lo:[0,1] neg_hi:[0,1]
	v_pk_mul_f32 v[84:85], v[246:247], v[84:85] op_sel:[1,0]
	v_pk_fma_f32 v[84:85], v[84:85], v[88:89], v[92:93]
	v_pk_add_f32 v[16:17], v[16:17], v[84:85]
	v_pk_add_f32 v[86:87], v[86:87], v[246:247] op_sel_hi:[1,0] neg_lo:[0,1] neg_hi:[0,1]
	v_pk_mul_f32 v[86:87], v[246:247], v[86:87] op_sel:[1,0]
	v_pk_fma_f32 v[86:87], v[86:87], v[90:91], v[94:95]
	v_pk_add_f32 v[18:19], v[18:19], v[86:87]
	v_pk_add_f32 v[104:105], v[104:105], v[20:21]
	v_pk_fma_f32 v[106:107], v[20:21], v[20:21], v[106:107]
	v_pk_add_f32 v[104:105], v[104:105], v[22:23]
	v_pk_fma_f32 v[106:107], v[22:23], v[22:23], v[106:107]
	v_pk_add_f32 v[104:105], v[104:105], v[16:17]
	v_pk_fma_f32 v[106:107], v[16:17], v[16:17], v[106:107]
	v_pk_add_f32 v[104:105], v[104:105], v[18:19]
	v_pk_fma_f32 v[106:107], v[18:19], v[18:19], v[106:107]
	v_add_f32_e32 v108, v104, v105
	v_add_f32_e32 v109, v106, v107
	s_nop 0
	ds_bpermute_b32 v104, v110, v108
	ds_bpermute_b32 v105, v110, v109
	s_waitcnt lgkmcnt(0)
	v_pk_add_f32 v[108:109], v[108:109], v[104:105]
	s_nop 0
	ds_bpermute_b32 v104, v111, v108
	ds_bpermute_b32 v105, v111, v109
	s_waitcnt lgkmcnt(0)
	v_pk_add_f32 v[108:109], v[108:109], v[104:105]
	ds_write_b64 v252, v[108:109] offset:5120
	s_waitcnt vmcnt(1)
	v_lshlrev_b32_e32 v80, 16, v222
	v_and_b32_e32 v81, 0xffff0000, v222
	v_lshlrev_b32_e32 v82, 16, v223
	v_and_b32_e32 v83, 0xffff0000, v223
	v_lshlrev_b32_e32 v84, 16, v224
	v_and_b32_e32 v85, 0xffff0000, v224
	v_lshlrev_b32_e32 v86, 16, v225
	v_and_b32_e32 v87, 0xffff0000, v225
	v_pk_add_f32 v[80:81], v[80:81], v[248:249] op_sel_hi:[1,0] neg_lo:[0,1] neg_hi:[0,1]
	v_pk_mul_f32 v[80:81], v[248:249], v[80:81] op_sel:[1,0]
	v_pk_fma_f32 v[80:81], v[80:81], v[120:121], v[116:117]
	v_pk_add_f32 v[12:13], v[12:13], v[80:81]
	v_pk_add_f32 v[82:83], v[82:83], v[248:249] op_sel_hi:[1,0] neg_lo:[0,1] neg_hi:[0,1]
	v_pk_mul_f32 v[82:83], v[248:249], v[82:83] op_sel:[1,0]
	v_pk_fma_f32 v[82:83], v[82:83], v[122:123], v[118:119]
	v_pk_add_f32 v[14:15], v[14:15], v[82:83]
	v_pk_add_f32 v[84:85], v[84:85], v[248:249] op_sel_hi:[1,0] neg_lo:[0,1] neg_hi:[0,1]
	v_pk_mul_f32 v[84:85], v[248:249], v[84:85] op_sel:[1,0]
	v_pk_fma_f32 v[84:85], v[84:85], v[112:113], v[124:125]
	v_pk_add_f32 v[8:9], v[8:9], v[84:85]
	v_pk_add_f32 v[86:87], v[86:87], v[248:249] op_sel_hi:[1,0] neg_lo:[0,1] neg_hi:[0,1]
	v_pk_mul_f32 v[86:87], v[248:249], v[86:87] op_sel:[1,0]
	v_pk_fma_f32 v[86:87], v[86:87], v[114:115], v[126:127]
	v_pk_add_f32 v[10:11], v[10:11], v[86:87]
	v_pk_mul_f32 v[106:107], v[12:13], v[12:13]
	v_pk_add_f32 v[104:105], v[12:13], v[14:15]
	v_pk_fma_f32 v[106:107], v[14:15], v[14:15], v[106:107]
	v_pk_add_f32 v[104:105], v[104:105], v[8:9]
	v_pk_fma_f32 v[106:107], v[8:9], v[8:9], v[106:107]
	v_pk_add_f32 v[104:105], v[104:105], v[10:11]
	v_pk_fma_f32 v[106:107], v[10:11], v[10:11], v[106:107]
	s_waitcnt vmcnt(0)
; #define EPI_FOR_ROWS for (int ai = 0; ai < 2; ++ai) _Pragma("unroll") for (int m = 0; m < 4; ++m)
;     __device__ __forceinline__ void operator()(const f32x4 (&acc)[2][2][4][2], const Unit& u, int wr, int wc, int fr_, int fq_, LAS unsigned char* ldsx) const {
;     ...
;         EPI_FOR_ROWS {
;             const int rl = ai * HALF + wr * 64 + m * 16 + fr; const size_t row = (size_t)u.row0 + rl;
;             float mean = 0.f, rstd = 0.f; if constexpr (CONS) { const f32x2 st = X[rl]; mean = st.x; rstd = st.y; }
;             float s = 0.f, ss = 0.f;
; #pragma unroll
;             for (int bj = 0; bj < 2; ++bj) piece(row, colb + bj * HALF, acc[ai][bj][m][0], acc[ai][bj][m][1], av[bj][0], av[bj][1], bv[bj][0], bv[bj][1], cv[bj][0], cv[bj][1], mean, rstd, s, ss);
;             if constexpr (PROD) { s += __shfl_xor(s, 16); ss += __shfl_xor(ss, 16); s += __shfl_xor(s, 32); ss += __shfl_xor(ss, 32);
;                 if (fq == 0) st_out[row * 16 + (u.col0 >> 8) * 4 + wc] = (f32x2){s, ss}; }
; __device__ __forceinline__ void ln_f32_inplace_phase(const Frame& F0, float* Y, const float* gam, const float* bet) {
;     ...
;             const float mean = wave_sum(s) * (1.f / DM); float s2 = 0.f;
; #pragma unroll
;             for (int q = 0; q < 4; ++q) { v[h][q] = v[h][q] - mean; s2 += (v[h][q][0] * v[h][q][0] + v[h][q][1] * v[h][q][1]) + (v[h][q][2] * v[h][q][2] + v[h][q][3] * v[h][q][3]); }
;             const float rstd = __builtin_amdgcn_rsqf(wave_sum(s2) * (1.f / DM) + LN_EPS);
	v_lshlrev_b32_e32 v80, 16, v226
	v_and_b32_e32 v81, 0xffff0000, v226
	v_lshlrev_b32_e32 v82, 16, v227
	v_and_b32_e32 v83, 0xffff0000, v227
	v_lshlrev_b32_e32 v84, 16, v228
	v_and_b32_e32 v85, 0xffff0000, v228
	v_lshlrev_b32_e32 v86, 16, v229
	v_and_b32_e32 v87, 0xffff0000, v229
	v_pk_add_f32 v[80:81], v[80:81], v[248:249] op_sel_hi:[1,0] neg_lo:[0,1] neg_hi:[0,1]
	v_pk_mul_f32 v[80:81], v[248:249], v[80:81] op_sel:[1,0]
	v_pk_fma_f32 v[80:81], v[80:81], v[96:97], v[100:101]
	v_pk_add_f32 v[4:5], v[4:5], v[80:81]
	v_pk_add_f32 v[82:83], v[82:83], v[248:249] op_sel_hi:[1,0] neg_lo:[0,1] neg_hi:[0,1]
	v_pk_mul_f32 v[82:83], v[248:249], v[82:83] op_sel:[1,0]
	v_pk_fma_f32 v[82:83], v[82:83], v[98:99], v[102:103]
	v_pk_add_f32 v[6:7], v[6:7], v[82:83]
	v_pk_add_f32 v[84:85], v[84:85], v[248:249] op_sel_hi:[1,0] neg_lo:[0,1] neg_hi:[0,1]
	v_pk_mul_f32 v[84:85], v[248:249], v[84:85] op_sel:[1,0]
	v_pk_fma_f32 v[84:85], v[84:85], v[88:89], v[92:93]
	v_pk_add_f32 v[0:1], v[0:1], v[84:85]
	v_pk_add_f32 v[86:87], v[86:87], v[248:249] op_sel_hi:[1,0] neg_lo:[0,1] neg_hi:[0,1]
	v_pk_mul_f32 v[86:87], v[248:249], v[86:87] op_sel:[1,0]
	v_pk_fma_f32 v[86:87], v[86:87], v[90:91], v[94:95]
	v_pk_add_f32 v[2:3], v[2:3], v[86:87]
	v_pk_add_f32 v[104:105], v[104:105], v[4:5]
	v_pk_fma_f32 v[106:107], v[4:5], v[4:5], v[106:107]
	v_pk_add_f32 v[104:105], v[104:105], v[6:7]
	v_pk_fma_f32 v[106:107], v[6:7], v[6:7], v[106:107]
	v_pk_add_f32 v[104:105], v[104:105], v[0:1]
	v_pk_fma_f32 v[106:107], v[0:1], v[0:1], v[106:107]
	v_pk_add_f32 v[104:105], v[104:105], v[2:3]
	v_pk_fma_f32 v[106:107], v[2:3], v[2:3], v[106:107]
	v_add_f32_e32 v108, v104, v105
	v_add_f32_e32 v109, v106, v107
	s_nop 0
	ds_bpermute_b32 v104, v110, v108
	ds_bpermute_b32 v105, v110, v109
	s_waitcnt lgkmcnt(0)
	v_pk_add_f32 v[108:109], v[108:109], v[104:105]
	s_nop 0
	ds_bpermute_b32 v104, v111, v108
	ds_bpermute_b32 v105, v111, v109
	s_waitcnt lgkmcnt(0)
	v_pk_add_f32 v[108:109], v[108:109], v[104:105]
	ds_write_b64 v252, v[108:109] offset:5632
	s_waitcnt lgkmcnt(0)
	s_barrier
	s_add_u32 s98, s58, 0x1c000000
	s_addc_u32 s99, s59, 0
	v_readfirstlane_b32 s100, v202
	s_cmp_lt_u32 s100, 0x100
	s_cbranch_scc0 .Lln3_nopub
	v_lshlrev_b32_e32 v80, 5, v202
	v_add_u32_e32 v80, 0x21000, v80
	ds_read_b128 v[84:87], v80
	ds_read_b128 v[88:91], v80 offset:16
	v_add_u32_e32 v81, s20, v202
	v_lshlrev_b32_e32 v81, 5, v81
	v_mov_b32_e32 v82, s30
	v_lshrrev_b32_e32 v82, 5, v82
	v_add_u32_e32 v81, v81, v82
	s_waitcnt lgkmcnt(0)
	v_pk_add_f32 v[84:85], v[84:85], v[86:87]
	v_pk_add_f32 v[88:89], v[88:89], v[90:91]
	v_pk_add_f32 v[84:85], v[84:85], v[88:89]
	global_store_dwordx2 v81, v[84:85], s[98:99] sc0 sc1
.Lln3_nopub:
	s_waitcnt vmcnt(0)
	s_barrier
	v_cmp_eq_u32_e64 s[100:101], 0, v202
	s_mov_b64 exec, s[100:101]
	s_cbranch_execz .Lln3_skip
	v_mov_b32_e32 v80, s20
	v_lshrrev_b32_e32 v80, 8, v80
	v_lshlrev_b32_e32 v80, 2, v80
	v_add_u32_e32 v80, 0x3800, v80
	v_mov_b32_e32 v81, 1
	global_atomic_add v80, v81, s[58:59]
	s_mov_b32 s100, 0
.Lln3_poll:
	global_load_dword v82, v80, s[58:59] sc1
	s_waitcnt vmcnt(0)
	v_readfirstlane_b32 s101, v82
	s_cmp_ge_u32 s101, 4
	s_cbranch_scc1 .Lln3_skip
	s_add_u32 s100, s100, 1
	s_cmp_lt_u32 s100, 0x40000
	s_cbranch_scc0 .Lln3_skip
	s_sleep 1
	s_branch .Lln3_poll
.Lln3_skip:
	s_mov_b64 exec, -1
	s_barrier
	v_lshrrev_b32_e32 v80, 1, v202
	v_and_b32_e32 v81, 1, v202
	v_add_u32_e32 v82, s20, v80
	v_lshlrev_b32_e32 v82, 5, v82
	v_lshl_add_u32 v82, v81, 4, v82
	global_load_dwordx4 v[84:87], v82, s[98:99] sc0 sc1
	global_load_dwordx4 v[112:115], v196, s[52:53]
	global_load_dwordx4 v[116:119], v196, s[52:53] offset:16
	global_load_dwordx4 v[120:123], v196, s[52:53] offset:512
	global_load_dwordx4 v[124:127], v196, s[52:53] offset:528
	global_load_dwordx4 v[96:99], v196, s[54:55]
	global_load_dwordx4 v[100:103], v196, s[54:55] offset:16
	global_load_dwordx4 v[104:107], v196, s[54:55] offset:512
	global_load_dwordx4 v[108:111], v196, s[54:55] offset:528
	s_waitcnt vmcnt(8)
	v_pk_add_f32 v[84:85], v[84:85], v[86:87]
	s_nop 1
	v_add_f32_dpp v86, v84, v84 quad_perm:[1,0,3,2] row_mask:0xf bank_mask:0xf
	v_add_f32_dpp v87, v85, v85 quad_perm:[1,0,3,2] row_mask:0xf bank_mask:0xf
	v_mul_f32_e32 v88, 0x3a800000, v86
	v_mul_f32_e32 v89, 0x3a800000, v87
	v_fma_f32 v89, -v88, v88, v89
	v_max_f32_e32 v89, 0, v89
	v_add_f32_e32 v89, 0x3727c5ac, v89
	v_rsq_f32_e32 v89, v89
	v_lshlrev_b32_e32 v90, 3, v80
	v_add_u32_e32 v90, 0x21000, v90
	s_nop 0
	ds_write_b64 v90, v[88:89]
	s_waitcnt lgkmcnt(0)
	s_barrier
; __device__ __forceinline__ void ln_f32_inplace_phase(const Frame& F0, float* Y, const float* gam, const float* bet) {
;     ...
;             const float mean = wave_sum(s) * (1.f / DM); float s2 = 0.f;
; #pragma unroll
;             for (int q = 0; q < 4; ++q) { v[h][q] = v[h][q] - mean; s2 += (v[h][q][0] * v[h][q][0] + v[h][q][1] * v[h][q][1]) + (v[h][q][2] * v[h][q][2] + v[h][q][3] * v[h][q][3]); }
;             const float rstd = __builtin_amdgcn_rsqf(wave_sum(s2) * (1.f / DM) + LN_EPS);
;             if (h == 0 || ok1) {
;                 float* yo = Y + (size_t)(h == 0 ? m0 : m1) * DM;
; #pragma unroll
;                 for (int q = 0; q < 4; ++q) __builtin_nontemporal_store(v[h][q] * rstd * g4[q] + b4[q], (f32x4*)(yo + q * 256 + F.lane * 4));
	v_lshlrev_b32_e32 v90, 3, v198
	v_add_u32_e32 v90, 0x21000, v90
	ds_read_b64 v[210:211], v90 offset:0
	v_add_u32_e32 v80, 0x0, v198
	v_add_u32_e32 v80, s20, v80
	v_lshlrev_b32_e32 v80, 12, v80
	v_add_u32_e32 v80, v80, v196
	ds_read_b64 v[212:213], v90 offset:128
	v_add_u32_e32 v81, 0x10, v198
	v_add_u32_e32 v81, s20, v81
	v_lshlrev_b32_e32 v81, 12, v81
	v_add_u32_e32 v81, v81, v196
	ds_read_b64 v[214:215], v90 offset:256
	v_add_u32_e32 v82, 0x20, v198
	v_add_u32_e32 v82, s20, v82
	v_lshlrev_b32_e32 v82, 12, v82
	v_add_u32_e32 v82, v82, v196
	ds_read_b64 v[216:217], v90 offset:384
	v_add_u32_e32 v83, 0x30, v198
	v_add_u32_e32 v83, s20, v83
	v_lshlrev_b32_e32 v83, 12, v83
	v_add_u32_e32 v83, v83, v196
	ds_read_b64 v[218:219], v90 offset:1024
	v_add_u32_e32 v84, 0x80, v198
	v_add_u32_e32 v84, s20, v84
	v_lshlrev_b32_e32 v84, 12, v84
	v_add_u32_e32 v84, v84, v196
	ds_read_b64 v[220:221], v90 offset:1152
	v_add_u32_e32 v85, 0x90, v198
	v_add_u32_e32 v85, s20, v85
	v_lshlrev_b32_e32 v85, 12, v85
	v_add_u32_e32 v85, v85, v196
	ds_read_b64 v[222:223], v90 offset:1280
	v_add_u32_e32 v86, 0xa0, v198
	v_add_u32_e32 v86, s20, v86
	v_lshlrev_b32_e32 v86, 12, v86
	v_add_u32_e32 v86, v86, v196
	ds_read_b64 v[224:225], v90 offset:1408
	v_add_u32_e32 v87, 0xb0, v198
	v_add_u32_e32 v87, s20, v87
	v_lshlrev_b32_e32 v87, 12, v87
	v_add_u32_e32 v87, v87, v196
	s_waitcnt vmcnt(0) lgkmcnt(0)
	v_pk_add_f32 v[172:173], v[172:173], v[210:211] op_sel_hi:[1,0] neg_lo:[0,1] neg_hi:[0,1]
	v_pk_mul_f32 v[172:173], v[210:211], v[172:173] op_sel:[1,0]
	v_pk_fma_f32 v[172:173], v[112:113], v[172:173], v[96:97]
	v_pk_add_f32 v[174:175], v[174:175], v[210:211] op_sel_hi:[1,0] neg_lo:[0,1] neg_hi:[0,1]
	v_pk_mul_f32 v[174:175], v[210:211], v[174:175] op_sel:[1,0]
	v_pk_fma_f32 v[174:175], v[114:115], v[174:175], v[98:99]
	v_pk_add_f32 v[168:169], v[168:169], v[210:211] op_sel_hi:[1,0] neg_lo:[0,1] neg_hi:[0,1]
	v_pk_mul_f32 v[168:169], v[210:211], v[168:169] op_sel:[1,0]
	v_pk_fma_f32 v[168:169], v[116:117], v[168:169], v[100:101]
	v_pk_add_f32 v[170:171], v[170:171], v[210:211] op_sel_hi:[1,0] neg_lo:[0,1] neg_hi:[0,1]
	v_pk_mul_f32 v[170:171], v[210:211], v[170:171] op_sel:[1,0]
	v_pk_fma_f32 v[170:171], v[118:119], v[170:171], v[102:103]
	global_store_dwordx4 v80, v[172:175], s[56:57] nt
	global_store_dwordx4 v80, v[168:171], s[56:57] offset:16 nt
	v_pk_add_f32 v[164:165], v[164:165], v[210:211] op_sel_hi:[1,0] neg_lo:[0,1] neg_hi:[0,1]
	v_pk_mul_f32 v[164:165], v[210:211], v[164:165] op_sel:[1,0]
	v_pk_fma_f32 v[164:165], v[120:121], v[164:165], v[104:105]
	v_pk_add_f32 v[166:167], v[166:167], v[210:211] op_sel_hi:[1,0] neg_lo:[0,1] neg_hi:[0,1]
	v_pk_mul_f32 v[166:167], v[210:211], v[166:167] op_sel:[1,0]
	v_pk_fma_f32 v[166:167], v[122:123], v[166:167], v[106:107]
	v_pk_add_f32 v[160:161], v[160:161], v[210:211] op_sel_hi:[1,0] neg_lo:[0,1] neg_hi:[0,1]
	v_pk_mul_f32 v[160:161], v[210:211], v[160:161] op_sel:[1,0]
	v_pk_fma_f32 v[160:161], v[124:125], v[160:161], v[108:109]
	v_pk_add_f32 v[162:163], v[162:163], v[210:211] op_sel_hi:[1,0] neg_lo:[0,1] neg_hi:[0,1]
	v_pk_mul_f32 v[162:163], v[210:211], v[162:163] op_sel:[1,0]
	v_pk_fma_f32 v[162:163], v[126:127], v[162:163], v[110:111]
	global_store_dwordx4 v80, v[164:167], s[56:57] offset:512 nt
	global_store_dwordx4 v80, v[160:163], s[56:57] offset:528 nt
	v_pk_add_f32 v[156:157], v[156:157], v[212:213] op_sel_hi:[1,0] neg_lo:[0,1] neg_hi:[0,1]
	v_pk_mul_f32 v[156:157], v[212:213], v[156:157] op_sel:[1,0]
	v_pk_fma_f32 v[156:157], v[112:113], v[156:157], v[96:97]
	v_pk_add_f32 v[158:159], v[158:159], v[212:213] op_sel_hi:[1,0] neg_lo:[0,1] neg_hi:[0,1]
	v_pk_mul_f32 v[158:159], v[212:213], v[158:159] op_sel:[1,0]
	v_pk_fma_f32 v[158:159], v[114:115], v[158:159], v[98:99]
	v_pk_add_f32 v[152:153], v[152:153], v[212:213] op_sel_hi:[1,0] neg_lo:[0,1] neg_hi:[0,1]
	v_pk_mul_f32 v[152:153], v[212:213], v[152:153] op_sel:[1,0]
	v_pk_fma_f32 v[152:153], v[116:117], v[152:153], v[100:101]
	v_pk_add_f32 v[154:155], v[154:155], v[212:213] op_sel_hi:[1,0] neg_lo:[0,1] neg_hi:[0,1]
	v_pk_mul_f32 v[154:155], v[212:213], v[154:155] op_sel:[1,0]
	v_pk_fma_f32 v[154:155], v[118:119], v[154:155], v[102:103]
	global_store_dwordx4 v81, v[156:159], s[56:57] nt
	global_store_dwordx4 v81, v[152:155], s[56:57] offset:16 nt
	v_pk_add_f32 v[148:149], v[148:149], v[212:213] op_sel_hi:[1,0] neg_lo:[0,1] neg_hi:[0,1]
	v_pk_mul_f32 v[148:149], v[212:213], v[148:149] op_sel:[1,0]
	v_pk_fma_f32 v[148:149], v[120:121], v[148:149], v[104:105]
	v_pk_add_f32 v[150:151], v[150:151], v[212:213] op_sel_hi:[1,0] neg_lo:[0,1] neg_hi:[0,1]
	v_pk_mul_f32 v[150:151], v[212:213], v[150:151] op_sel:[1,0]
	v_pk_fma_f32 v[150:151], v[122:123], v[150:151], v[106:107]
	v_pk_add_f32 v[144:145], v[144:145], v[212:213] op_sel_hi:[1,0] neg_lo:[0,1] neg_hi:[0,1]
	v_pk_mul_f32 v[144:145], v[212:213], v[144:145] op_sel:[1,0]
	v_pk_fma_f32 v[144:145], v[124:125], v[144:145], v[108:109]
	v_pk_add_f32 v[146:147], v[146:147], v[212:213] op_sel_hi:[1,0] neg_lo:[0,1] neg_hi:[0,1]
	v_pk_mul_f32 v[146:147], v[212:213], v[146:147] op_sel:[1,0]
	v_pk_fma_f32 v[146:147], v[126:127], v[146:147], v[110:111]
	global_store_dwordx4 v81, v[148:151], s[56:57] offset:512 nt
	global_store_dwordx4 v81, v[144:147], s[56:57] offset:528 nt
	v_pk_add_f32 v[140:141], v[140:141], v[214:215] op_sel_hi:[1,0] neg_lo:[0,1] neg_hi:[0,1]
	v_pk_mul_f32 v[140:141], v[214:215], v[140:141] op_sel:[1,0]
	v_pk_fma_f32 v[140:141], v[112:113], v[140:141], v[96:97]
	v_pk_add_f32 v[142:143], v[142:143], v[214:215] op_sel_hi:[1,0] neg_lo:[0,1] neg_hi:[0,1]
	v_pk_mul_f32 v[142:143], v[214:215], v[142:143] op_sel:[1,0]
; __device__ __forceinline__ void ln_f32_inplace_phase(const Frame& F0, float* Y, const float* gam, const float* bet) {
;     ...
;             if (h == 0 || ok1) {
;                 float* yo = Y + (size_t)(h == 0 ? m0 : m1) * DM;
; #pragma unroll
;                 for (int q = 0; q < 4; ++q) __builtin_nontemporal_store(v[h][q] * rstd * g4[q] + b4[q], (f32x4*)(yo + q * 256 + F.lane * 4));
	v_pk_fma_f32 v[142:143], v[114:115], v[142:143], v[98:99]
	v_pk_add_f32 v[136:137], v[136:137], v[214:215] op_sel_hi:[1,0] neg_lo:[0,1] neg_hi:[0,1]
	v_pk_mul_f32 v[136:137], v[214:215], v[136:137] op_sel:[1,0]
	v_pk_fma_f32 v[136:137], v[116:117], v[136:137], v[100:101]
	v_pk_add_f32 v[138:139], v[138:139], v[214:215] op_sel_hi:[1,0] neg_lo:[0,1] neg_hi:[0,1]
	v_pk_mul_f32 v[138:139], v[214:215], v[138:139] op_sel:[1,0]
	v_pk_fma_f32 v[138:139], v[118:119], v[138:139], v[102:103]
	global_store_dwordx4 v82, v[140:143], s[56:57] nt
	global_store_dwordx4 v82, v[136:139], s[56:57] offset:16 nt
	v_pk_add_f32 v[132:133], v[132:133], v[214:215] op_sel_hi:[1,0] neg_lo:[0,1] neg_hi:[0,1]
	v_pk_mul_f32 v[132:133], v[214:215], v[132:133] op_sel:[1,0]
	v_pk_fma_f32 v[132:133], v[120:121], v[132:133], v[104:105]
	v_pk_add_f32 v[134:135], v[134:135], v[214:215] op_sel_hi:[1,0] neg_lo:[0,1] neg_hi:[0,1]
	v_pk_mul_f32 v[134:135], v[214:215], v[134:135] op_sel:[1,0]
	v_pk_fma_f32 v[134:135], v[122:123], v[134:135], v[106:107]
	v_pk_add_f32 v[128:129], v[128:129], v[214:215] op_sel_hi:[1,0] neg_lo:[0,1] neg_hi:[0,1]
	v_pk_mul_f32 v[128:129], v[214:215], v[128:129] op_sel:[1,0]
	v_pk_fma_f32 v[128:129], v[124:125], v[128:129], v[108:109]
	v_pk_add_f32 v[130:131], v[130:131], v[214:215] op_sel_hi:[1,0] neg_lo:[0,1] neg_hi:[0,1]
	v_pk_mul_f32 v[130:131], v[214:215], v[130:131] op_sel:[1,0]
	v_pk_fma_f32 v[130:131], v[126:127], v[130:131], v[110:111]
	global_store_dwordx4 v82, v[132:135], s[56:57] offset:512 nt
	global_store_dwordx4 v82, v[128:131], s[56:57] offset:528 nt
	v_pk_add_f32 v[76:77], v[76:77], v[216:217] op_sel_hi:[1,0] neg_lo:[0,1] neg_hi:[0,1]
	v_pk_mul_f32 v[76:77], v[216:217], v[76:77] op_sel:[1,0]
	v_pk_fma_f32 v[76:77], v[112:113], v[76:77], v[96:97]
	v_pk_add_f32 v[78:79], v[78:79], v[216:217] op_sel_hi:[1,0] neg_lo:[0,1] neg_hi:[0,1]
	v_pk_mul_f32 v[78:79], v[216:217], v[78:79] op_sel:[1,0]
	v_pk_fma_f32 v[78:79], v[114:115], v[78:79], v[98:99]
	v_pk_add_f32 v[72:73], v[72:73], v[216:217] op_sel_hi:[1,0] neg_lo:[0,1] neg_hi:[0,1]
	v_pk_mul_f32 v[72:73], v[216:217], v[72:73] op_sel:[1,0]
	v_pk_fma_f32 v[72:73], v[116:117], v[72:73], v[100:101]
	v_pk_add_f32 v[74:75], v[74:75], v[216:217] op_sel_hi:[1,0] neg_lo:[0,1] neg_hi:[0,1]
	v_pk_mul_f32 v[74:75], v[216:217], v[74:75] op_sel:[1,0]
	v_pk_fma_f32 v[74:75], v[118:119], v[74:75], v[102:103]
	global_store_dwordx4 v83, v[76:79], s[56:57] nt
	global_store_dwordx4 v83, v[72:75], s[56:57] offset:16 nt
	v_pk_add_f32 v[68:69], v[68:69], v[216:217] op_sel_hi:[1,0] neg_lo:[0,1] neg_hi:[0,1]
	v_pk_mul_f32 v[68:69], v[216:217], v[68:69] op_sel:[1,0]
	v_pk_fma_f32 v[68:69], v[120:121], v[68:69], v[104:105]
	v_pk_add_f32 v[70:71], v[70:71], v[216:217] op_sel_hi:[1,0] neg_lo:[0,1] neg_hi:[0,1]
	v_pk_mul_f32 v[70:71], v[216:217], v[70:71] op_sel:[1,0]
	v_pk_fma_f32 v[70:71], v[122:123], v[70:71], v[106:107]
	v_pk_add_f32 v[64:65], v[64:65], v[216:217] op_sel_hi:[1,0] neg_lo:[0,1] neg_hi:[0,1]
	v_pk_mul_f32 v[64:65], v[216:217], v[64:65] op_sel:[1,0]
	v_pk_fma_f32 v[64:65], v[124:125], v[64:65], v[108:109]
	v_pk_add_f32 v[66:67], v[66:67], v[216:217] op_sel_hi:[1,0] neg_lo:[0,1] neg_hi:[0,1]
	v_pk_mul_f32 v[66:67], v[216:217], v[66:67] op_sel:[1,0]
	v_pk_fma_f32 v[66:67], v[126:127], v[66:67], v[110:111]
	global_store_dwordx4 v83, v[68:71], s[56:57] offset:512 nt
	global_store_dwordx4 v83, v[64:67], s[56:57] offset:528 nt
	v_pk_add_f32 v[60:61], v[60:61], v[218:219] op_sel_hi:[1,0] neg_lo:[0,1] neg_hi:[0,1]
	v_pk_mul_f32 v[60:61], v[218:219], v[60:61] op_sel:[1,0]
	v_pk_fma_f32 v[60:61], v[112:113], v[60:61], v[96:97]
	v_pk_add_f32 v[62:63], v[62:63], v[218:219] op_sel_hi:[1,0] neg_lo:[0,1] neg_hi:[0,1]
	v_pk_mul_f32 v[62:63], v[218:219], v[62:63] op_sel:[1,0]
	v_pk_fma_f32 v[62:63], v[114:115], v[62:63], v[98:99]
	v_pk_add_f32 v[56:57], v[56:57], v[218:219] op_sel_hi:[1,0] neg_lo:[0,1] neg_hi:[0,1]
	v_pk_mul_f32 v[56:57], v[218:219], v[56:57] op_sel:[1,0]
	v_pk_fma_f32 v[56:57], v[116:117], v[56:57], v[100:101]
	v_pk_add_f32 v[58:59], v[58:59], v[218:219] op_sel_hi:[1,0] neg_lo:[0,1] neg_hi:[0,1]
	v_pk_mul_f32 v[58:59], v[218:219], v[58:59] op_sel:[1,0]
	v_pk_fma_f32 v[58:59], v[118:119], v[58:59], v[102:103]
	global_store_dwordx4 v84, v[60:63], s[56:57] nt
	global_store_dwordx4 v84, v[56:59], s[56:57] offset:16 nt
	v_pk_add_f32 v[52:53], v[52:53], v[218:219] op_sel_hi:[1,0] neg_lo:[0,1] neg_hi:[0,1]
	v_pk_mul_f32 v[52:53], v[218:219], v[52:53] op_sel:[1,0]
	v_pk_fma_f32 v[52:53], v[120:121], v[52:53], v[104:105]
	v_pk_add_f32 v[54:55], v[54:55], v[218:219] op_sel_hi:[1,0] neg_lo:[0,1] neg_hi:[0,1]
	v_pk_mul_f32 v[54:55], v[218:219], v[54:55] op_sel:[1,0]
	v_pk_fma_f32 v[54:55], v[122:123], v[54:55], v[106:107]
	v_pk_add_f32 v[48:49], v[48:49], v[218:219] op_sel_hi:[1,0] neg_lo:[0,1] neg_hi:[0,1]
	v_pk_mul_f32 v[48:49], v[218:219], v[48:49] op_sel:[1,0]
	v_pk_fma_f32 v[48:49], v[124:125], v[48:49], v[108:109]
	v_pk_add_f32 v[50:51], v[50:51], v[218:219] op_sel_hi:[1,0] neg_lo:[0,1] neg_hi:[0,1]
	v_pk_mul_f32 v[50:51], v[218:219], v[50:51] op_sel:[1,0]
	v_pk_fma_f32 v[50:51], v[126:127], v[50:51], v[110:111]
	global_store_dwordx4 v84, v[52:55], s[56:57] offset:512 nt
	global_store_dwordx4 v84, v[48:51], s[56:57] offset:528 nt
	v_pk_add_f32 v[44:45], v[44:45], v[220:221] op_sel_hi:[1,0] neg_lo:[0,1] neg_hi:[0,1]
	v_pk_mul_f32 v[44:45], v[220:221], v[44:45] op_sel:[1,0]
; __device__ __forceinline__ void ln_f32_inplace_phase(const Frame& F0, float* Y, const float* gam, const float* bet) {
;     ...
;             if (h == 0 || ok1) {
;                 float* yo = Y + (size_t)(h == 0 ? m0 : m1) * DM;
; #pragma unroll
;                 for (int q = 0; q < 4; ++q) __builtin_nontemporal_store(v[h][q] * rstd * g4[q] + b4[q], (f32x4*)(yo + q * 256 + F.lane * 4));
	v_pk_fma_f32 v[44:45], v[112:113], v[44:45], v[96:97]
	v_pk_add_f32 v[46:47], v[46:47], v[220:221] op_sel_hi:[1,0] neg_lo:[0,1] neg_hi:[0,1]
	v_pk_mul_f32 v[46:47], v[220:221], v[46:47] op_sel:[1,0]
	v_pk_fma_f32 v[46:47], v[114:115], v[46:47], v[98:99]
	v_pk_add_f32 v[40:41], v[40:41], v[220:221] op_sel_hi:[1,0] neg_lo:[0,1] neg_hi:[0,1]
	v_pk_mul_f32 v[40:41], v[220:221], v[40:41] op_sel:[1,0]
	v_pk_fma_f32 v[40:41], v[116:117], v[40:41], v[100:101]
	v_pk_add_f32 v[42:43], v[42:43], v[220:221] op_sel_hi:[1,0] neg_lo:[0,1] neg_hi:[0,1]
	v_pk_mul_f32 v[42:43], v[220:221], v[42:43] op_sel:[1,0]
	v_pk_fma_f32 v[42:43], v[118:119], v[42:43], v[102:103]
	global_store_dwordx4 v85, v[44:47], s[56:57] nt
	global_store_dwordx4 v85, v[40:43], s[56:57] offset:16 nt
	v_pk_add_f32 v[36:37], v[36:37], v[220:221] op_sel_hi:[1,0] neg_lo:[0,1] neg_hi:[0,1]
	v_pk_mul_f32 v[36:37], v[220:221], v[36:37] op_sel:[1,0]
	v_pk_fma_f32 v[36:37], v[120:121], v[36:37], v[104:105]
	v_pk_add_f32 v[38:39], v[38:39], v[220:221] op_sel_hi:[1,0] neg_lo:[0,1] neg_hi:[0,1]
	v_pk_mul_f32 v[38:39], v[220:221], v[38:39] op_sel:[1,0]
	v_pk_fma_f32 v[38:39], v[122:123], v[38:39], v[106:107]
	v_pk_add_f32 v[32:33], v[32:33], v[220:221] op_sel_hi:[1,0] neg_lo:[0,1] neg_hi:[0,1]
	v_pk_mul_f32 v[32:33], v[220:221], v[32:33] op_sel:[1,0]
	v_pk_fma_f32 v[32:33], v[124:125], v[32:33], v[108:109]
	v_pk_add_f32 v[34:35], v[34:35], v[220:221] op_sel_hi:[1,0] neg_lo:[0,1] neg_hi:[0,1]
	v_pk_mul_f32 v[34:35], v[220:221], v[34:35] op_sel:[1,0]
	v_pk_fma_f32 v[34:35], v[126:127], v[34:35], v[110:111]
	global_store_dwordx4 v85, v[36:39], s[56:57] offset:512 nt
	global_store_dwordx4 v85, v[32:35], s[56:57] offset:528 nt
	v_pk_add_f32 v[28:29], v[28:29], v[222:223] op_sel_hi:[1,0] neg_lo:[0,1] neg_hi:[0,1]
	v_pk_mul_f32 v[28:29], v[222:223], v[28:29] op_sel:[1,0]
	v_pk_fma_f32 v[28:29], v[112:113], v[28:29], v[96:97]
	v_pk_add_f32 v[30:31], v[30:31], v[222:223] op_sel_hi:[1,0] neg_lo:[0,1] neg_hi:[0,1]
	v_pk_mul_f32 v[30:31], v[222:223], v[30:31] op_sel:[1,0]
	v_pk_fma_f32 v[30:31], v[114:115], v[30:31], v[98:99]
	v_pk_add_f32 v[24:25], v[24:25], v[222:223] op_sel_hi:[1,0] neg_lo:[0,1] neg_hi:[0,1]
	v_pk_mul_f32 v[24:25], v[222:223], v[24:25] op_sel:[1,0]
	v_pk_fma_f32 v[24:25], v[116:117], v[24:25], v[100:101]
	v_pk_add_f32 v[26:27], v[26:27], v[222:223] op_sel_hi:[1,0] neg_lo:[0,1] neg_hi:[0,1]
	v_pk_mul_f32 v[26:27], v[222:223], v[26:27] op_sel:[1,0]
	v_pk_fma_f32 v[26:27], v[118:119], v[26:27], v[102:103]
	global_store_dwordx4 v86, v[28:31], s[56:57] nt
	global_store_dwordx4 v86, v[24:27], s[56:57] offset:16 nt
	v_pk_add_f32 v[20:21], v[20:21], v[222:223] op_sel_hi:[1,0] neg_lo:[0,1] neg_hi:[0,1]
	v_pk_mul_f32 v[20:21], v[222:223], v[20:21] op_sel:[1,0]
	v_pk_fma_f32 v[20:21], v[120:121], v[20:21], v[104:105]
	v_pk_add_f32 v[22:23], v[22:23], v[222:223] op_sel_hi:[1,0] neg_lo:[0,1] neg_hi:[0,1]
	v_pk_mul_f32 v[22:23], v[222:223], v[22:23] op_sel:[1,0]
	v_pk_fma_f32 v[22:23], v[122:123], v[22:23], v[106:107]
	v_pk_add_f32 v[16:17], v[16:17], v[222:223] op_sel_hi:[1,0] neg_lo:[0,1] neg_hi:[0,1]
	v_pk_mul_f32 v[16:17], v[222:223], v[16:17] op_sel:[1,0]
	v_pk_fma_f32 v[16:17], v[124:125], v[16:17], v[108:109]
	v_pk_add_f32 v[18:19], v[18:19], v[222:223] op_sel_hi:[1,0] neg_lo:[0,1] neg_hi:[0,1]
	v_pk_mul_f32 v[18:19], v[222:223], v[18:19] op_sel:[1,0]
	v_pk_fma_f32 v[18:19], v[126:127], v[18:19], v[110:111]
	global_store_dwordx4 v86, v[20:23], s[56:57] offset:512 nt
	global_store_dwordx4 v86, v[16:19], s[56:57] offset:528 nt
	v_pk_add_f32 v[12:13], v[12:13], v[224:225] op_sel_hi:[1,0] neg_lo:[0,1] neg_hi:[0,1]
	v_pk_mul_f32 v[12:13], v[224:225], v[12:13] op_sel:[1,0]
	v_pk_fma_f32 v[12:13], v[112:113], v[12:13], v[96:97]
	v_pk_add_f32 v[14:15], v[14:15], v[224:225] op_sel_hi:[1,0] neg_lo:[0,1] neg_hi:[0,1]
	v_pk_mul_f32 v[14:15], v[224:225], v[14:15] op_sel:[1,0]
	v_pk_fma_f32 v[14:15], v[114:115], v[14:15], v[98:99]
	v_pk_add_f32 v[8:9], v[8:9], v[224:225] op_sel_hi:[1,0] neg_lo:[0,1] neg_hi:[0,1]
	v_pk_mul_f32 v[8:9], v[224:225], v[8:9] op_sel:[1,0]
	v_pk_fma_f32 v[8:9], v[116:117], v[8:9], v[100:101]
	v_pk_add_f32 v[10:11], v[10:11], v[224:225] op_sel_hi:[1,0] neg_lo:[0,1] neg_hi:[0,1]
	v_pk_mul_f32 v[10:11], v[224:225], v[10:11] op_sel:[1,0]
	v_pk_fma_f32 v[10:11], v[118:119], v[10:11], v[102:103]
	global_store_dwordx4 v87, v[12:15], s[56:57] nt
	global_store_dwordx4 v87, v[8:11], s[56:57] offset:16 nt
	v_pk_add_f32 v[4:5], v[4:5], v[224:225] op_sel_hi:[1,0] neg_lo:[0,1] neg_hi:[0,1]
	v_pk_mul_f32 v[4:5], v[224:225], v[4:5] op_sel:[1,0]
	v_pk_fma_f32 v[4:5], v[120:121], v[4:5], v[104:105]
	v_pk_add_f32 v[6:7], v[6:7], v[224:225] op_sel_hi:[1,0] neg_lo:[0,1] neg_hi:[0,1]
	v_pk_mul_f32 v[6:7], v[224:225], v[6:7] op_sel:[1,0]
	v_pk_fma_f32 v[6:7], v[122:123], v[6:7], v[106:107]
	v_pk_add_f32 v[0:1], v[0:1], v[224:225] op_sel_hi:[1,0] neg_lo:[0,1] neg_hi:[0,1]
	v_pk_mul_f32 v[0:1], v[224:225], v[0:1] op_sel:[1,0]
	v_pk_fma_f32 v[0:1], v[124:125], v[0:1], v[108:109]
	v_pk_add_f32 v[2:3], v[2:3], v[224:225] op_sel_hi:[1,0] neg_lo:[0,1] neg_hi:[0,1]
	v_pk_mul_f32 v[2:3], v[224:225], v[2:3] op_sel:[1,0]
	v_pk_fma_f32 v[2:3], v[126:127], v[2:3], v[110:111]
	global_store_dwordx4 v87, v[4:7], s[56:57] offset:512 nt
	global_store_dwordx4 v87, v[0:3], s[56:57] offset:528 nt
	s_cbranch_vccnz .LBB0_1469
	s_andn2_b64 vcc, exec, s[4:5]
	s_cbranch_vccnz .LBB0_1468
	s_barrier
	s_branch .LBB0_1468

; __device__ __forceinline__ Frame fresh(const Frame& F0) { Frame F = F0; int t = threadIdx.x; asm volatile("" : "+v"(t)); F.tid = t; F.lane = t & 63; F.wave = __builtin_amdgcn_readfirstlane(t >> 6); return F; }
; __device__ __forceinline__ void ln_f32_inplace_phase(const Frame& F0, float* Y, const float* gam, const float* bet) {
;     const Frame F = fresh(F0);
;     const int gw = F.vcu * 8 + F.wave, NGW = F.G * 8;
;     f32x4 g4[4], b4[4];
; #pragma unroll
;     for (int q = 0; q < 4; ++q) { g4[q] = *(const f32x4*)(gam + q * 256 + F.lane * 4); b4[q] = *(const f32x4*)(bet + q * 256 + F.lane * 4); }
;     for (int m0 = gw; m0 < R; m0 += 2 * NGW) {
;         const int m1 = m0 + NGW; const bool ok1 = m1 < R; const int mm1 = ok1 ? m1 : m0;
.LBB0_1541:
	s_or_b64 exec, exec, s[0:1]
	s_waitcnt lgkmcnt(0)
	s_barrier
	v_readlane_b32 s1, v254, 56
	v_readfirstlane_b32 s0, v202
	s_ashr_i32 s0, s0, 6
	s_add_i32 s2, s0, s1
	s_add_i32 s2, s2, 0x8000
	s_cmp_gt_i32 s2, 0x80ff
	s_cbranch_scc1 .LBB0_1546
	v_lshlrev_b32_e32 v0, 4, v202
	v_and_b32_e32 v32, 0x3f0, v0
	global_load_dwordx4 v[0:3], v32, s[52:53]
	global_load_dwordx4 v[4:7], v32, s[54:55]
	global_load_dwordx4 v[8:11], v32, s[52:53] offset:1024
	global_load_dwordx4 v[12:15], v32, s[54:55] offset:1024
	global_load_dwordx4 v[16:19], v32, s[52:53] offset:2048
	global_load_dwordx4 v[20:23], v32, s[54:55] offset:2048
	global_load_dwordx4 v[24:27], v32, s[52:53] offset:3072
	global_load_dwordx4 v[28:31], v32, s[54:55] offset:3072
	v_mov_b32_e32 v33, 0
	v_lshl_add_u64 v[64:65], s[56:57], 0, v[32:33]
	v_mbcnt_lo_u32_b32 v32, -1, 0
	v_mbcnt_hi_u32_b32 v32, -1, v32
	v_and_b32_e32 v33, 64, v32
	v_add_u32_e32 v33, 64, v33
	v_xor_b32_e32 v34, 1, v32
	v_cmp_lt_i32_e32 vcc, v34, v33
	v_mov_b32_e32 v74, 0x3727c5ac
	s_nop 0
	v_cndmask_b32_e32 v34, v32, v34, vcc
	v_lshlrev_b32_e32 v68, 2, v34
	v_xor_b32_e32 v34, 2, v32
	v_cmp_lt_i32_e32 vcc, v34, v33
	s_nop 1
	v_cndmask_b32_e32 v34, v32, v34, vcc
	v_lshlrev_b32_e32 v69, 2, v34
	v_xor_b32_e32 v34, 4, v32
	v_cmp_lt_i32_e32 vcc, v34, v33
	s_nop 1
	v_cndmask_b32_e32 v34, v32, v34, vcc
	v_lshlrev_b32_e32 v70, 2, v34
	v_xor_b32_e32 v34, 8, v32
	v_cmp_lt_i32_e32 vcc, v34, v33
	s_nop 1
	v_cndmask_b32_e32 v34, v32, v34, vcc
	v_lshlrev_b32_e32 v71, 2, v34
	v_xor_b32_e32 v34, 16, v32
	v_cmp_lt_i32_e32 vcc, v34, v33
	s_nop 1
	v_cndmask_b32_e32 v34, v32, v34, vcc
	v_lshlrev_b32_e32 v72, 2, v34
	v_xor_b32_e32 v34, 32, v32
	v_cmp_lt_i32_e32 vcc, v34, v33
	s_nop 1
	v_cndmask_b32_e32 v32, v32, v34, vcc
	v_lshlrev_b32_e32 v73, 2, v32
	s_branch .LBB0_1544

; __global__ void __launch_bounds__(512, 2) fwd_megakernel(Params p) {
	.amdhsa_kernel _Z14fwd_megakernel6Params
		.amdhsa_group_segment_fixed_size 0
		.amdhsa_private_segment_fixed_size 0
		.amdhsa_kernarg_size 576
		.amdhsa_user_sgpr_count 2
		.amdhsa_user_sgpr_dispatch_ptr 0
		.amdhsa_user_sgpr_queue_ptr 0
		.amdhsa_user_sgpr_kernarg_segment_ptr 1
		.amdhsa_user_sgpr_dispatch_id 0
		.amdhsa_user_sgpr_kernarg_preload_length 0
		.amdhsa_user_sgpr_kernarg_preload_offset 0
		.amdhsa_user_sgpr_private_segment_size 0
		.amdhsa_uses_dynamic_stack 0
		.amdhsa_enable_private_segment 0
		.amdhsa_system_sgpr_workgroup_id_x 1
		.amdhsa_system_sgpr_workgroup_id_y 0
		.amdhsa_system_sgpr_workgroup_id_z 0
		.amdhsa_system_sgpr_workgroup_info 0
		.amdhsa_system_vgpr_workitem_id 2
		.amdhsa_next_free_vgpr 256
		.amdhsa_next_free_sgpr 102
		.amdhsa_accum_offset 256
		.amdhsa_reserve_vcc 1
		.amdhsa_float_round_mode_32 0
		.amdhsa_float_round_mode_16_64 0
		.amdhsa_float_denorm_mode_32 3
		.amdhsa_float_denorm_mode_16_64 3
		.amdhsa_dx10_clamp 1
		.amdhsa_ieee_mode 1
		.amdhsa_fp16_overflow 0
		.amdhsa_tg_split 0
		.amdhsa_exception_fp_ieee_invalid_op 0
		.amdhsa_exception_fp_denorm_src 0
		.amdhsa_exception_fp_ieee_div_zero 0
		.amdhsa_exception_fp_ieee_overflow 0
		.amdhsa_exception_fp_ieee_underflow 0
		.amdhsa_exception_fp_ieee_inexact 0
		.amdhsa_exception_int_div_zero 0
	.end_amdhsa_kernel

; __global__ void __launch_bounds__(512, 2) fwd_megakernel(Params p) {
amdhsa.kernels:
  - .agpr_count:     0
    .args:
      - .offset:         0
        .size:           320
        .value_kind:     by_value
      - .offset:         320
        .size:           4
        .value_kind:     hidden_block_count_x
      - .offset:         324
        .size:           4
        .value_kind:     hidden_block_count_y
      - .offset:         328
        .size:           4
        .value_kind:     hidden_block_count_z
      - .offset:         332
        .size:           2
        .value_kind:     hidden_group_size_x
      - .offset:         334
        .size:           2
        .value_kind:     hidden_group_size_y
      - .offset:         336
        .size:           2
        .value_kind:     hidden_group_size_z
      - .offset:         338
        .size:           2
        .value_kind:     hidden_remainder_x
      - .offset:         340
        .size:           2
        .value_kind:     hidden_remainder_y
      - .offset:         342
        .size:           2
        .value_kind:     hidden_remainder_z
      - .offset:         360
        .size:           8
        .value_kind:     hidden_global_offset_x
      - .offset:         368
        .size:           8
        .value_kind:     hidden_global_offset_y
      - .offset:         376
        .size:           8
        .value_kind:     hidden_global_offset_z
      - .offset:         384
        .size:           2
        .value_kind:     hidden_grid_dims
      - .offset:         408
        .size:           8
        .value_kind:     hidden_multigrid_sync_arg
      - .offset:         440
        .size:           4
        .value_kind:     hidden_dynamic_lds_size
    .group_segment_fixed_size: 0
    .kernarg_segment_align: 8
    .kernarg_segment_size: 576
    .language:       OpenCL C
    .language_version:
      - 2
      - 0
    .max_flat_workgroup_size: 512
    .name:           _Z14fwd_megakernel6Params
    .private_segment_fixed_size: 0
    .sgpr_count:     108
    .sgpr_spill_count: 96
    .symbol:         _Z14fwd_megakernel6Params.kd
    .uniform_work_group_size: 1
    .uses_dynamic_stack: false
    .vgpr_count:     256
    .vgpr_spill_count: 0
    .wavefront_size: 64
